# v82 + the five K-loop head labels aligned to 64 bytes (.p2align 6)
# speedup vs baseline: 1.0045x; 1.0045x over previous
; #define PG8_STAGE(bufoff, gbase, voff) do { _Pragma("unroll") for (int _i = 0; _i < 2; ++_i) \
;         __builtin_amdgcn_global_load_lds((const unsigned*)((const char*)(gbase) + (voff)[_i]), (PG8_LAS unsigned*)(lds + (bufoff) + ldsw + _i * 8192), 16, 0, 0); } while (0)
; #define PG8_LDA(dst, b, h) do { _Pragma("unroll") for (int m = 0; m < 4; ++m) _Pragma("unroll") for (int k = 0; k < 2; ++k) dst[m][k] = *(const PG8_LAS bf16x8*)(lds + PG8_SA(b, h) + aoff + m * 2048 + k * 1024); } while (0)
; #define PG8_LDB(dst, b, h) do { _Pragma("unroll") for (int n = 0; n < 2; ++n) _Pragma("unroll") for (int k = 0; k < 2; ++k) dst[n][k] = *(const PG8_LAS bf16x8*)(lds + PG8_SB(b, h) + boff + n * 2048 + k * 1024); } while (0)
; #define PG8_MMA(ai, bj, At, Bt) do { __builtin_amdgcn_s_setprio(1); _Pragma("unroll") for (int m = 0; m < 4; ++m) _Pragma("unroll") for (int n = 0; n < 2; ++n) _Pragma("unroll") for (int k = 0; k < 2; ++k) \
;         acc[ai][bj][m][n] = mma16<Epi::I8>(Bt[n][k], At[m][k], acc[ai][bj][m][n]); __builtin_amdgcn_s_setprio(0); } while (0)
; #define PG8_WAIT_V(n) asm volatile("s_waitcnt vmcnt(" #n ")" ::: "memory")
; #define PG8_WAIT_L(n) asm volatile("s_waitcnt lgkmcnt(" #n ")" ::: "memory")
; #define PG8_BAR __builtin_amdgcn_s_barrier()
; template <class Epi, class Sched, bool ALIGN_EPI = false, bool SP2 = false>
; __device__ __forceinline__ void gemm_phase(PG8_LAS unsigned char* lds, const Gemm g, const Sched& S, const Epi& E) {
;     ...
;             const bool last = (t == nt - 2);
;             const char* a1 = cA + (size_t)(t + 1) * kstep;
;             const char* a2 = last ? nA : cA + (size_t)(t + 2) * kstep; const char* b2 = last ? nB : cB + (size_t)(t + 2) * kstep;
;             const char* a3 = a2 + kstep; const char* b3 = b2 + kstep;
;             if (last && has_next) S.a_ready(nxt);
;             if constexpr (SP2) {
;             PG8_LDB(B0, 0, 0); PG8_LDB(B1, 0, 1); PG8_SCHED; PG8_LDA(At, 0, 0); PG8_STAGE(PG8_SA(1, 1), a1 + hstep, voffA);
;             PG8_WAIT_V(8); PG8_WAIT_L(0); PG8_BAR; PG8_MMA(0, 0, At, B0); PG8_MMA(0, 1, At, B1); PG8_BAR; PG8_SCHED;
;             PG8_LDA(At, 0, 1); PG8_STAGE(PG8_SB(0, 0), b2, voffB); PG8_STAGE(PG8_SB(0, 1), b2 + hstep, voffB); PG8_STAGE(PG8_SA(0, 0), a2, voffA);
;             PG8_WAIT_V(8); PG8_WAIT_L(0); PG8_BAR; PG8_MMA(1, 0, At, B0); PG8_MMA(1, 1, At, B1); PG8_BAR; PG8_SCHED;
.Lpeel80:
	s_add_u32 s8, s0, 0x100
	s_addc_u32 s9, s1, 0
	s_add_i32 vcc_hi, 0, 0x10000
	s_cmp_eq_u32 vcc_lo, 12
	s_cselect_b32 s13, s66, s9
	s_cselect_b32 s12, s67, s8
	s_cselect_b32 s7, s82, s97
	s_cselect_b32 s6, s83, s96
	s_add_i32 s4, 0, 0x14000
	v_add_u32_e32 v38, vcc_hi, v242
	v_add_u32_e32 v158, s4, v242
	ds_read_b128 v[18:21], v38
	ds_read_b128 v[22:25], v38 offset:1024
	ds_read_b128 v[34:37], v38 offset:2048
	ds_read_b128 v[38:41], v38 offset:3072
	ds_read_b128 v[130:133], v158
	ds_read_b128 v[134:137], v158 offset:1024
	ds_read_b128 v[154:157], v158 offset:2048
	ds_read_b128 v[158:161], v158 offset:3072
	s_add_i32 m0, s11, 0xc000
	ds_read_b128 v[162:165], v243
	ds_read_b128 v[166:169], v243 offset:1024
	ds_read_b128 v[170:173], v243 offset:2048
	ds_read_b128 v[174:177], v243 offset:3072
	ds_read_b128 v[178:181], v243 offset:4096
	ds_read_b128 v[182:185], v243 offset:5120
	ds_read_b128 v[186:189], v243 offset:6144
	ds_read_b128 v[190:193], v243 offset:7168
	global_load_lds_dwordx4 v216, s[0:1]
	s_add_i32 m0, s11, 0xe000
	s_nop 0
	global_load_lds_dwordx4 v218, s[0:1]
	s_waitcnt vmcnt(8)
	s_waitcnt lgkmcnt(0)
	s_barrier
	s_waitcnt lgkmcnt(0)
	v_mfma_i32_16x16x64_i8 v[150:153], v[18:21], v[162:165], 0
	v_mfma_i32_16x16x64_i8 v[146:149], v[34:37], v[162:165], 0
	v_mfma_i32_16x16x64_i8 v[110:113], v[34:37], v[170:173], 0
	v_mfma_i32_16x16x64_i8 v[118:121], v[18:21], v[170:173], 0
	v_mfma_i32_16x16x64_i8 v[54:57], v[18:21], v[178:181], 0
	v_mfma_i32_16x16x64_i8 v[30:33], v[34:37], v[178:181], 0
	v_mfma_i32_16x16x64_i8 v[58:61], v[34:37], v[186:189], 0
	v_mfma_i32_16x16x64_i8 v[94:97], v[18:21], v[186:189], 0
	v_mfma_i32_16x16x64_i8 v[150:153], v[22:25], v[166:169], v[150:153]
	v_mfma_i32_16x16x64_i8 v[146:149], v[38:41], v[166:169], v[146:149]
	v_mfma_i32_16x16x64_i8 v[110:113], v[38:41], v[174:177], v[110:113]
	v_mfma_i32_16x16x64_i8 v[118:121], v[22:25], v[174:177], v[118:121]
	v_mfma_i32_16x16x64_i8 v[54:57], v[22:25], v[182:185], v[54:57]
	v_mfma_i32_16x16x64_i8 v[30:33], v[38:41], v[182:185], v[30:33]
	v_mfma_i32_16x16x64_i8 v[58:61], v[38:41], v[190:193], v[58:61]
	v_mfma_i32_16x16x64_i8 v[94:97], v[22:25], v[190:193], v[94:97]
	v_mfma_i32_16x16x64_i8 v[142:145], v[130:133], v[162:165], 0
	v_mfma_i32_16x16x64_i8 v[138:141], v[154:157], v[162:165], 0
	v_mfma_i32_16x16x64_i8 v[98:101], v[154:157], v[170:173], 0
	v_mfma_i32_16x16x64_i8 v[102:105], v[130:133], v[170:173], 0
	v_mfma_i32_16x16x64_i8 v[42:45], v[130:133], v[178:181], 0
	v_mfma_i32_16x16x64_i8 v[26:29], v[154:157], v[178:181], 0
	v_mfma_i32_16x16x64_i8 v[62:65], v[154:157], v[186:189], 0
	v_mfma_i32_16x16x64_i8 v[78:81], v[130:133], v[186:189], 0
	v_mfma_i32_16x16x64_i8 v[142:145], v[134:137], v[166:169], v[142:145]
	v_mfma_i32_16x16x64_i8 v[138:141], v[158:161], v[166:169], v[138:141]
	v_mfma_i32_16x16x64_i8 v[98:101], v[158:161], v[174:177], v[98:101]
	v_mfma_i32_16x16x64_i8 v[102:105], v[134:137], v[174:177], v[102:105]
	v_mfma_i32_16x16x64_i8 v[42:45], v[134:137], v[182:185], v[42:45]
	v_mfma_i32_16x16x64_i8 v[26:29], v[158:161], v[182:185], v[26:29]
	v_mfma_i32_16x16x64_i8 v[62:65], v[158:161], v[190:193], v[62:65]
	v_mfma_i32_16x16x64_i8 v[78:81], v[134:137], v[190:193], v[78:81]
	s_barrier
	s_add_i32 s0, vcc_hi, s69
	v_lshl_add_u64 v[198:199], s[6:7], 0, v[0:1]
	s_mov_b32 m0, s0
	ds_read_b128 v[162:165], v243 offset:16384
	ds_read_b128 v[166:169], v243 offset:17408
	ds_read_b128 v[170:173], v243 offset:18432
	ds_read_b128 v[174:177], v243 offset:19456
	ds_read_b128 v[178:181], v243 offset:20480
	ds_read_b128 v[182:185], v243 offset:21504
	ds_read_b128 v[186:189], v243 offset:22528
	ds_read_b128 v[190:193], v243 offset:23552
	global_load_lds_dwordx4 v[198:199], off
	s_add_i32 m0, s0, 0x2000
	s_add_u32 s0, s6, 0x40000
	v_lshl_add_u64 v[200:201], s[6:7], 0, v[214:215]
	s_addc_u32 s1, s7, 0
	s_add_i32 s4, s4, s69
	global_load_lds_dwordx4 v[200:201], off
	s_mov_b32 m0, s4
	v_lshl_add_u64 v[206:207], s[12:13], 0, v[210:211]
	global_load_lds_dwordx4 v0, s[0:1]
	s_add_i32 m0, s4, 0x2000
	v_lshl_add_u64 v[220:221], s[12:13], 0, v[212:213]
	global_load_lds_dwordx4 v214, s[0:1]
	s_mov_b32 m0, s11
	s_nop 0
	global_load_lds_dwordx4 v[206:207], off
	s_mov_b32 m0, s71
	s_nop 0
	global_load_lds_dwordx4 v[220:221], off
	s_waitcnt vmcnt(8)
	s_waitcnt lgkmcnt(0)
	s_barrier
	s_waitcnt lgkmcnt(0)
	v_mfma_i32_16x16x64_i8 v[106:109], v[18:21], v[162:165], 0
	v_mfma_i32_16x16x64_i8 v[46:49], v[34:37], v[162:165], 0
	v_mfma_i32_16x16x64_i8 v[6:9], v[34:37], v[170:173], 0
	v_mfma_i32_16x16x64_i8 v[14:17], v[18:21], v[170:173], 0
	v_mfma_i32_16x16x64_i8 v[90:93], v[18:21], v[178:181], 0
	v_mfma_i32_16x16x64_i8 v[86:89], v[34:37], v[178:181], 0
	v_mfma_i32_16x16x64_i8 v[18:21], v[18:21], v[186:189], 0
	v_mfma_i32_16x16x64_i8 v[106:109], v[22:25], v[166:169], v[106:109]
	v_mfma_i32_16x16x64_i8 v[46:49], v[38:41], v[166:169], v[46:49]
	v_mfma_i32_16x16x64_i8 v[6:9], v[38:41], v[174:177], v[6:9]
	v_mfma_i32_16x16x64_i8 v[14:17], v[22:25], v[174:177], v[14:17]
	v_mfma_i32_16x16x64_i8 v[90:93], v[22:25], v[182:185], v[90:93]
	v_mfma_i32_16x16x64_i8 v[86:89], v[38:41], v[182:185], v[86:89]
	v_mfma_i32_16x16x64_i8 v[18:21], v[22:25], v[190:193], v[18:21]
	v_mfma_i32_16x16x64_i8 v[22:25], v[34:37], v[186:189], 0
	v_mfma_i32_16x16x64_i8 v[22:25], v[38:41], v[190:193], v[22:25]
	v_mfma_i32_16x16x64_i8 v[38:41], v[154:157], v[162:165], 0
	v_mfma_i32_16x16x64_i8 v[2:5], v[154:157], v[170:173], 0
	v_mfma_i32_16x16x64_i8 v[10:13], v[130:133], v[170:173], 0
	v_mfma_i32_16x16x64_i8 v[50:53], v[130:133], v[178:181], 0
	v_mfma_i32_16x16x64_i8 v[34:37], v[130:133], v[162:165], 0
	v_mfma_i32_16x16x64_i8 v[82:85], v[134:137], v[182:185], v[50:53]
	v_mfma_i32_16x16x64_i8 v[50:53], v[154:157], v[178:181], 0
	v_mfma_i32_16x16x64_i8 v[2:5], v[158:161], v[174:177], v[2:5]
	v_mfma_i32_16x16x64_i8 v[10:13], v[134:137], v[174:177], v[10:13]
	v_mfma_i32_16x16x64_i8 v[38:41], v[158:161], v[166:169], v[38:41]
	v_mfma_i32_16x16x64_i8 v[34:37], v[134:137], v[166:169], v[34:37]
	v_mfma_i32_16x16x64_i8 v[74:77], v[158:161], v[182:185], v[50:53]
	v_mfma_i32_16x16x64_i8 v[50:53], v[130:133], v[186:189], 0
	v_mfma_i32_16x16x64_i8 v[122:125], v[134:137], v[190:193], v[50:53]
	v_mfma_i32_16x16x64_i8 v[50:53], v[154:157], v[186:189], 0
	v_mfma_i32_16x16x64_i8 v[70:73], v[158:161], v[190:193], v[50:53]
	s_barrier
; #define PG8_STAGE(bufoff, gbase, voff) do { _Pragma("unroll") for (int _i = 0; _i < 2; ++_i) \
;         __builtin_amdgcn_global_load_lds((const unsigned*)((const char*)(gbase) + (voff)[_i]), (PG8_LAS unsigned*)(lds + (bufoff) + ldsw + _i * 8192), 16, 0, 0); } while (0)
; #define PG8_LDA(dst, b, h) do { _Pragma("unroll") for (int m = 0; m < 4; ++m) _Pragma("unroll") for (int k = 0; k < 2; ++k) dst[m][k] = *(const PG8_LAS bf16x8*)(lds + PG8_SA(b, h) + aoff + m * 2048 + k * 1024); } while (0)
; #define PG8_LDB(dst, b, h) do { _Pragma("unroll") for (int n = 0; n < 2; ++n) _Pragma("unroll") for (int k = 0; k < 2; ++k) dst[n][k] = *(const PG8_LAS bf16x8*)(lds + PG8_SB(b, h) + boff + n * 2048 + k * 1024); } while (0)
; #define PG8_MMA(ai, bj, At, Bt) do { __builtin_amdgcn_s_setprio(1); _Pragma("unroll") for (int m = 0; m < 4; ++m) _Pragma("unroll") for (int n = 0; n < 2; ++n) _Pragma("unroll") for (int k = 0; k < 2; ++k) \
;         acc[ai][bj][m][n] = mma16<Epi::I8>(Bt[n][k], At[m][k], acc[ai][bj][m][n]); __builtin_amdgcn_s_setprio(0); } while (0)
; #define PG8_WAIT_V(n) asm volatile("s_waitcnt vmcnt(" #n ")" ::: "memory")
; #define PG8_WAIT_L(n) asm volatile("s_waitcnt lgkmcnt(" #n ")" ::: "memory")
; #define PG8_BAR __builtin_amdgcn_s_barrier()
; #define PG8_SCHED __builtin_amdgcn_sched_barrier(0)
; template <class Epi, class Sched, bool ALIGN_EPI = false, bool SP2 = false>
; __device__ __forceinline__ void gemm_phase(PG8_LAS unsigned char* lds, const Gemm g, const Sched& S, const Epi& E) {
;     ...
;             PG8_LDB(B0, 1, 0); PG8_LDB(B1, 1, 1); PG8_SCHED; PG8_LDA(At, 1, 0); PG8_STAGE(PG8_SA(0, 1), a2 + hstep, voffA);
;             PG8_WAIT_V(8); PG8_WAIT_L(0); PG8_BAR; PG8_MMA(0, 0, At, B0); PG8_MMA(0, 1, At, B1); PG8_BAR; PG8_SCHED;
;             PG8_LDA(At, 1, 1); PG8_STAGE(PG8_SB(1, 0), b3, voffB); PG8_STAGE(PG8_SB(1, 1), b3 + hstep, voffB); PG8_STAGE(PG8_SA(1, 0), a3, voffA);
;             PG8_WAIT_V(8); PG8_WAIT_L(0); PG8_BAR; PG8_MMA(1, 0, At, B0); PG8_MMA(1, 1, At, B1); PG8_BAR; PG8_SCHED;
	s_add_i32 s4, 0, 0x18000
	v_add_u32_e32 v126, s4, v242
	s_add_i32 s5, 0, 0x1c000
	ds_read_b128 v[50:53], v126
	ds_read_b128 v[66:69], v126 offset:1024
	ds_read_b128 v[114:117], v126 offset:2048
	ds_read_b128 v[130:133], v126 offset:3072
	v_add_u32_e32 v126, s5, v242
	ds_read_b128 v[134:137], v126
	ds_read_b128 v[154:157], v126 offset:1024
	ds_read_b128 v[158:161], v126 offset:2048
	ds_read_b128 v[162:165], v126 offset:3072
	s_add_u32 s0, s12, 0x40000
	s_addc_u32 s1, s13, 0
	s_mov_b32 m0, s80
	ds_read_b128 v[126:129], v243 offset:32768
	ds_read_b128 v[166:169], v243 offset:33792
	ds_read_b128 v[170:173], v243 offset:34816
	ds_read_b128 v[174:177], v243 offset:35840
	ds_read_b128 v[178:181], v243 offset:36864
	ds_read_b128 v[182:185], v243 offset:37888
	ds_read_b128 v[186:189], v243 offset:38912
	ds_read_b128 v[190:193], v243 offset:39936
	global_load_lds_dwordx4 v210, s[0:1]
	s_mov_b32 m0, s81
	s_nop 0
	global_load_lds_dwordx4 v212, s[0:1]
	s_waitcnt vmcnt(8)
	s_waitcnt lgkmcnt(0)
	s_barrier
	s_waitcnt lgkmcnt(0)
	v_mfma_i32_16x16x64_i8 v[150:153], v[50:53], v[126:129], v[150:153]
	v_mfma_i32_16x16x64_i8 v[146:149], v[114:117], v[126:129], v[146:149]
	v_mfma_i32_16x16x64_i8 v[110:113], v[114:117], v[170:173], v[110:113]
	v_mfma_i32_16x16x64_i8 v[118:121], v[50:53], v[170:173], v[118:121]
	v_mfma_i32_16x16x64_i8 v[54:57], v[50:53], v[178:181], v[54:57]
	v_mfma_i32_16x16x64_i8 v[30:33], v[114:117], v[178:181], v[30:33]
	v_mfma_i32_16x16x64_i8 v[58:61], v[114:117], v[186:189], v[58:61]
	v_mfma_i32_16x16x64_i8 v[94:97], v[50:53], v[186:189], v[94:97]
	v_mfma_i32_16x16x64_i8 v[150:153], v[66:69], v[166:169], v[150:153]
	v_mfma_i32_16x16x64_i8 v[146:149], v[130:133], v[166:169], v[146:149]
	v_mfma_i32_16x16x64_i8 v[110:113], v[130:133], v[174:177], v[110:113]
	v_mfma_i32_16x16x64_i8 v[118:121], v[66:69], v[174:177], v[118:121]
	v_mfma_i32_16x16x64_i8 v[54:57], v[66:69], v[182:185], v[54:57]
	v_mfma_i32_16x16x64_i8 v[30:33], v[130:133], v[182:185], v[30:33]
	v_mfma_i32_16x16x64_i8 v[58:61], v[130:133], v[190:193], v[58:61]
	v_mfma_i32_16x16x64_i8 v[94:97], v[66:69], v[190:193], v[94:97]
	v_mfma_i32_16x16x64_i8 v[142:145], v[134:137], v[126:129], v[142:145]
	v_mfma_i32_16x16x64_i8 v[126:129], v[158:161], v[126:129], v[138:141]
	v_mfma_i32_16x16x64_i8 v[98:101], v[158:161], v[170:173], v[98:101]
	v_mfma_i32_16x16x64_i8 v[102:105], v[134:137], v[170:173], v[102:105]
	v_mfma_i32_16x16x64_i8 v[42:45], v[134:137], v[178:181], v[42:45]
	v_mfma_i32_16x16x64_i8 v[26:29], v[158:161], v[178:181], v[26:29]
	v_mfma_i32_16x16x64_i8 v[62:65], v[158:161], v[186:189], v[62:65]
	v_mfma_i32_16x16x64_i8 v[78:81], v[134:137], v[186:189], v[78:81]
	v_mfma_i32_16x16x64_i8 v[142:145], v[154:157], v[166:169], v[142:145]
	v_mfma_i32_16x16x64_i8 v[138:141], v[162:165], v[166:169], v[126:129]
	v_mfma_i32_16x16x64_i8 v[98:101], v[162:165], v[174:177], v[98:101]
	v_mfma_i32_16x16x64_i8 v[102:105], v[154:157], v[174:177], v[102:105]
	v_mfma_i32_16x16x64_i8 v[42:45], v[154:157], v[182:185], v[42:45]
	v_mfma_i32_16x16x64_i8 v[26:29], v[162:165], v[182:185], v[26:29]
	v_mfma_i32_16x16x64_i8 v[62:65], v[162:165], v[190:193], v[62:65]
	v_mfma_i32_16x16x64_i8 v[78:81], v[154:157], v[190:193], v[78:81]
	s_barrier
	s_add_i32 s0, s4, s69
	v_lshl_add_u64 v[126:127], v[198:199], 0, s[92:93]
	s_mov_b32 m0, s0
	ds_read_b128 v[166:169], v243 offset:49152
	ds_read_b128 v[170:173], v243 offset:50176
	ds_read_b128 v[174:177], v243 offset:51200
	ds_read_b128 v[178:181], v243 offset:52224
	ds_read_b128 v[182:185], v243 offset:53248
	ds_read_b128 v[186:189], v243 offset:54272
	ds_read_b128 v[190:193], v243 offset:55296
	ds_read_b128 v[194:197], v243 offset:56320
	global_load_lds_dwordx4 v[126:127], off
	s_add_i32 m0, s0, 0x2000
	s_add_u32 s0, s6, 0x40080
	v_lshl_add_u64 v[126:127], v[200:201], 0, s[92:93]
	s_addc_u32 s1, s7, 0
	s_add_i32 s4, s5, s69
	global_load_lds_dwordx4 v[126:127], off
	s_mov_b32 m0, s4
	s_nop 0
	global_load_lds_dwordx4 v0, s[0:1]
	s_add_i32 m0, s4, 0x2000
	s_nop 0
	global_load_lds_dwordx4 v214, s[0:1]
	v_lshl_add_u64 v[126:127], v[206:207], 0, s[92:93]
	s_mov_b32 m0, s84
	s_nop 0
	global_load_lds_dwordx4 v[126:127], off
	v_lshl_add_u64 v[126:127], v[220:221], 0, s[92:93]
	s_mov_b32 m0, s85
	s_nop 0
	global_load_lds_dwordx4 v[126:127], off
	s_waitcnt vmcnt(8)
	s_waitcnt lgkmcnt(0)
	s_barrier
	s_waitcnt lgkmcnt(0)
	v_mfma_i32_16x16x64_i8 v[18:21], v[50:53], v[190:193], v[18:21]
	v_mfma_i32_16x16x64_i8 v[106:109], v[50:53], v[166:169], v[106:109]
	v_mfma_i32_16x16x64_i8 v[46:49], v[114:117], v[166:169], v[46:49]
	v_mfma_i32_16x16x64_i8 v[6:9], v[114:117], v[174:177], v[6:9]
	v_mfma_i32_16x16x64_i8 v[14:17], v[50:53], v[174:177], v[14:17]
	v_mfma_i32_16x16x64_i8 v[90:93], v[50:53], v[182:185], v[90:93]
	v_mfma_i32_16x16x64_i8 v[86:89], v[114:117], v[182:185], v[86:89]
	v_mfma_i32_16x16x64_i8 v[126:129], v[66:69], v[194:197], v[18:21]
	v_mfma_i32_16x16x64_i8 v[106:109], v[66:69], v[170:173], v[106:109]
	v_mfma_i32_16x16x64_i8 v[46:49], v[130:133], v[170:173], v[46:49]
	v_mfma_i32_16x16x64_i8 v[6:9], v[130:133], v[178:181], v[6:9]
	v_mfma_i32_16x16x64_i8 v[14:17], v[66:69], v[178:181], v[14:17]
	v_mfma_i32_16x16x64_i8 v[90:93], v[66:69], v[186:189], v[90:93]
	v_mfma_i32_16x16x64_i8 v[86:89], v[130:133], v[186:189], v[86:89]
	v_mfma_i32_16x16x64_i8 v[18:21], v[114:117], v[190:193], v[22:25]
	v_mfma_i32_16x16x64_i8 v[66:69], v[130:133], v[194:197], v[18:21]
	v_mfma_i32_16x16x64_i8 v[18:21], v[134:137], v[166:169], v[34:37]
	v_mfma_i32_16x16x64_i8 v[10:13], v[134:137], v[174:177], v[10:13]
	v_mfma_i32_16x16x64_i8 v[2:5], v[158:161], v[174:177], v[2:5]
	v_mfma_i32_16x16x64_i8 v[114:117], v[154:157], v[170:173], v[18:21]
	v_mfma_i32_16x16x64_i8 v[18:21], v[158:161], v[166:169], v[38:41]
	v_mfma_i32_16x16x64_i8 v[50:53], v[162:165], v[170:173], v[18:21]
	v_mfma_i32_16x16x64_i8 v[18:21], v[134:137], v[182:185], v[82:85]
	v_mfma_i32_16x16x64_i8 v[10:13], v[154:157], v[178:181], v[10:13]
	v_mfma_i32_16x16x64_i8 v[2:5], v[162:165], v[178:181], v[2:5]
	v_mfma_i32_16x16x64_i8 v[82:85], v[154:157], v[186:189], v[18:21]
	v_mfma_i32_16x16x64_i8 v[18:21], v[158:161], v[182:185], v[74:77]
	v_mfma_i32_16x16x64_i8 v[74:77], v[162:165], v[186:189], v[18:21]
	v_mfma_i32_16x16x64_i8 v[18:21], v[134:137], v[190:193], v[122:125]
	v_mfma_i32_16x16x64_i8 v[122:125], v[154:157], v[194:197], v[18:21]
	v_mfma_i32_16x16x64_i8 v[18:21], v[158:161], v[190:193], v[70:73]
	v_mfma_i32_16x16x64_i8 v[70:73], v[162:165], v[194:197], v[18:21]
	s_barrier
	s_add_i32 vcc_lo, vcc_lo, 2
	s_add_u32 s96, s96, 0x100
	s_addc_u32 s97, s97, 0
	s_cmp_gt_u32 vcc_lo, 13
	s_mov_b64 s[0:1], s[8:9]
	s_cbranch_scc0 .LBB0_80
	s_branch .Lpeelx80
	.p2align	6

; #define PG8_STAGE(bufoff, gbase, voff) do { _Pragma("unroll") for (int _i = 0; _i < 2; ++_i) \
;         __builtin_amdgcn_global_load_lds((const unsigned*)((const char*)(gbase) + (voff)[_i]), (PG8_LAS unsigned*)(lds + (bufoff) + ldsw + _i * 8192), 16, 0, 0); } while (0)
; #define PG8_LDA(dst, b, h) do { _Pragma("unroll") for (int m = 0; m < 4; ++m) _Pragma("unroll") for (int k = 0; k < 2; ++k) dst[m][k] = *(const PG8_LAS bf16x8*)(lds + PG8_SA(b, h) + aoff + m * 2048 + k * 1024); } while (0)
; #define PG8_LDB(dst, b, h) do { _Pragma("unroll") for (int n = 0; n < 2; ++n) _Pragma("unroll") for (int k = 0; k < 2; ++k) dst[n][k] = *(const PG8_LAS bf16x8*)(lds + PG8_SB(b, h) + boff + n * 2048 + k * 1024); } while (0)
; #define PG8_MMA(ai, bj, At, Bt) do { __builtin_amdgcn_s_setprio(1); _Pragma("unroll") for (int m = 0; m < 4; ++m) _Pragma("unroll") for (int n = 0; n < 2; ++n) _Pragma("unroll") for (int k = 0; k < 2; ++k) \
;         acc[ai][bj][m][n] = mma16<Epi::I8>(Bt[n][k], At[m][k], acc[ai][bj][m][n]); __builtin_amdgcn_s_setprio(0); } while (0)
; #define PG8_WAIT_V(n) asm volatile("s_waitcnt vmcnt(" #n ")" ::: "memory")
; #define PG8_WAIT_L(n) asm volatile("s_waitcnt lgkmcnt(" #n ")" ::: "memory")
; #define PG8_BAR __builtin_amdgcn_s_barrier()
; template <class Epi, class Sched, bool ALIGN_EPI = false, bool SP2 = false>
; __device__ __forceinline__ void gemm_phase(PG8_LAS unsigned char* lds, const Gemm g, const Sched& S, const Epi& E) {
;     ...
;             const bool last = (t == nt - 2);
;             const char* a1 = cA + (size_t)(t + 1) * kstep;
;             const char* a2 = last ? nA : cA + (size_t)(t + 2) * kstep; const char* b2 = last ? nB : cB + (size_t)(t + 2) * kstep;
;             const char* a3 = a2 + kstep; const char* b3 = b2 + kstep;
;             if (last && has_next) S.a_ready(nxt);
;             if constexpr (SP2) {
;             PG8_LDB(B0, 0, 0); PG8_LDB(B1, 0, 1); PG8_SCHED; PG8_LDA(At, 0, 0); PG8_STAGE(PG8_SA(1, 1), a1 + hstep, voffA);
;             PG8_WAIT_V(8); PG8_WAIT_L(0); PG8_BAR; PG8_MMA(0, 0, At, B0); PG8_MMA(0, 1, At, B1); PG8_BAR; PG8_SCHED;
;             PG8_LDA(At, 0, 1); PG8_STAGE(PG8_SB(0, 0), b2, voffB); PG8_STAGE(PG8_SB(0, 1), b2 + hstep, voffB); PG8_STAGE(PG8_SA(0, 0), a2, voffA);
;             PG8_WAIT_V(8); PG8_WAIT_L(0); PG8_BAR; PG8_MMA(1, 0, At, B0); PG8_MMA(1, 1, At, B1); PG8_BAR; PG8_SCHED;
.Lpeel175:
	s_add_i32 vcc_lo, s8, 2
	s_add_u32 s4, s6, s98
	s_addc_u32 s5, s7, 0
	s_add_i32 vcc_hi, 0, 0x10000
	s_cmp_eq_u32 s13, s8
	s_cselect_b32 s9, s1, s5
	s_cselect_b32 s8, s0, s4
	s_cselect_b32 s5, s97, s85
	s_cselect_b32 s4, s96, s67
	s_add_i32 s84, 0, 0x14000
	v_add_u32_e32 v122, vcc_hi, v248
	v_add_u32_e32 v154, s84, v248
	ds_read_b128 v[98:101], v122
	ds_read_b128 v[102:105], v122 offset:1024
	ds_read_b128 v[114:117], v122 offset:2048
	ds_read_b128 v[122:125], v122 offset:3072
	ds_read_b128 v[130:133], v154
	ds_read_b128 v[138:141], v154 offset:1024
	ds_read_b128 v[146:149], v154 offset:2048
	ds_read_b128 v[154:157], v154 offset:3072
	v_lshl_add_u64 v[206:207], s[6:7], 0, v[200:201]
	s_add_i32 m0, s81, 0xc000
	ds_read_b128 v[162:165], v249
	ds_read_b128 v[166:169], v249 offset:1024
	ds_read_b128 v[170:173], v249 offset:2048
	ds_read_b128 v[174:177], v249 offset:3072
	ds_read_b128 v[178:181], v249 offset:4096
	ds_read_b128 v[182:185], v249 offset:5120
	ds_read_b128 v[186:189], v249 offset:6144
	ds_read_b128 v[190:193], v249 offset:7168
	global_load_lds_dwordx4 v[206:207], off
	v_lshl_add_u64 v[206:207], s[6:7], 0, v[210:211]
	s_add_i32 m0, s81, 0xe000
	s_nop 0
	global_load_lds_dwordx4 v[206:207], off
	s_waitcnt vmcnt(8)
	s_waitcnt lgkmcnt(0)
	s_barrier
	s_waitcnt lgkmcnt(0)
	v_mfma_f32_16x16x32_bf16 v[158:161], v[98:101], v[162:165], 0
	v_mfma_f32_16x16x32_bf16 v[150:153], v[114:117], v[162:165], 0
	v_mfma_f32_16x16x32_bf16 v[118:121], v[114:117], v[170:173], 0
	v_mfma_f32_16x16x32_bf16 v[126:129], v[98:101], v[170:173], 0
	v_mfma_f32_16x16x32_bf16 v[94:97], v[98:101], v[178:181], 0
	v_mfma_f32_16x16x32_bf16 v[90:93], v[114:117], v[178:181], 0
	v_mfma_f32_16x16x32_bf16 v[74:77], v[114:117], v[186:189], 0
	v_mfma_f32_16x16x32_bf16 v[78:81], v[98:101], v[186:189], 0
	v_mfma_f32_16x16x32_bf16 v[158:161], v[102:105], v[166:169], v[158:161]
	v_mfma_f32_16x16x32_bf16 v[150:153], v[122:125], v[166:169], v[150:153]
	v_mfma_f32_16x16x32_bf16 v[118:121], v[122:125], v[174:177], v[118:121]
	v_mfma_f32_16x16x32_bf16 v[126:129], v[102:105], v[174:177], v[126:129]
	v_mfma_f32_16x16x32_bf16 v[94:97], v[102:105], v[182:185], v[94:97]
	v_mfma_f32_16x16x32_bf16 v[90:93], v[122:125], v[182:185], v[90:93]
	v_mfma_f32_16x16x32_bf16 v[74:77], v[122:125], v[190:193], v[74:77]
	v_mfma_f32_16x16x32_bf16 v[78:81], v[102:105], v[190:193], v[78:81]
	v_mfma_f32_16x16x32_bf16 v[142:145], v[130:133], v[162:165], 0
	v_mfma_f32_16x16x32_bf16 v[134:137], v[146:149], v[162:165], 0
	v_mfma_f32_16x16x32_bf16 v[106:109], v[146:149], v[170:173], 0
	v_mfma_f32_16x16x32_bf16 v[110:113], v[130:133], v[170:173], 0
	v_mfma_f32_16x16x32_bf16 v[86:89], v[130:133], v[178:181], 0
	v_mfma_f32_16x16x32_bf16 v[82:85], v[146:149], v[178:181], 0
	v_mfma_f32_16x16x32_bf16 v[66:69], v[146:149], v[186:189], 0
	v_mfma_f32_16x16x32_bf16 v[70:73], v[130:133], v[186:189], 0
	v_mfma_f32_16x16x32_bf16 v[142:145], v[138:141], v[166:169], v[142:145]
	v_mfma_f32_16x16x32_bf16 v[134:137], v[154:157], v[166:169], v[134:137]
	v_mfma_f32_16x16x32_bf16 v[106:109], v[154:157], v[174:177], v[106:109]
	v_mfma_f32_16x16x32_bf16 v[110:113], v[138:141], v[174:177], v[110:113]
	v_mfma_f32_16x16x32_bf16 v[86:89], v[138:141], v[182:185], v[86:89]
	v_mfma_f32_16x16x32_bf16 v[82:85], v[154:157], v[182:185], v[82:85]
	v_mfma_f32_16x16x32_bf16 v[66:69], v[154:157], v[190:193], v[66:69]
	v_mfma_f32_16x16x32_bf16 v[70:73], v[138:141], v[190:193], v[70:73]
	s_barrier
	s_add_i32 vcc_hi, vcc_hi, s80
	v_lshl_add_u64 v[206:207], s[4:5], 0, v[0:1]
	s_mov_b32 m0, vcc_hi
	ds_read_b128 v[162:165], v249 offset:16384
	ds_read_b128 v[166:169], v249 offset:17408
	ds_read_b128 v[170:173], v249 offset:18432
	ds_read_b128 v[174:177], v249 offset:19456
	ds_read_b128 v[178:181], v249 offset:20480
	ds_read_b128 v[182:185], v249 offset:21504
	ds_read_b128 v[186:189], v249 offset:22528
	ds_read_b128 v[190:193], v249 offset:23552
	global_load_lds_dwordx4 v[206:207], off
	s_add_i32 m0, vcc_hi, 0x2000
	v_lshl_add_u64 v[212:213], s[4:5], 0, v[198:199]
	s_add_u32 s4, s4, s100
	s_addc_u32 s5, s5, 0
	s_add_i32 s84, s84, s80
	global_load_lds_dwordx4 v[212:213], off
	v_lshl_add_u64 v[214:215], s[4:5], 0, v[0:1]
	s_mov_b32 m0, s84
	v_lshl_add_u64 v[216:217], s[4:5], 0, v[198:199]
	global_load_lds_dwordx4 v[214:215], off
	s_add_i32 m0, s84, 0x2000
	v_lshl_add_u64 v[218:219], s[8:9], 0, v[194:195]
	global_load_lds_dwordx4 v[216:217], off
	s_mov_b32 m0, s81
	v_lshl_add_u64 v[220:221], s[8:9], 0, v[196:197]
	global_load_lds_dwordx4 v[218:219], off
	s_mov_b32 m0, s70
	s_nop 0
	global_load_lds_dwordx4 v[220:221], off
	s_waitcnt vmcnt(8)
	s_waitcnt lgkmcnt(0)
	s_barrier
; #define PG8_STAGE(bufoff, gbase, voff) do { _Pragma("unroll") for (int _i = 0; _i < 2; ++_i) \
;         __builtin_amdgcn_global_load_lds((const unsigned*)((const char*)(gbase) + (voff)[_i]), (PG8_LAS unsigned*)(lds + (bufoff) + ldsw + _i * 8192), 16, 0, 0); } while (0)
; #define PG8_LDA(dst, b, h) do { _Pragma("unroll") for (int m = 0; m < 4; ++m) _Pragma("unroll") for (int k = 0; k < 2; ++k) dst[m][k] = *(const PG8_LAS bf16x8*)(lds + PG8_SA(b, h) + aoff + m * 2048 + k * 1024); } while (0)
; #define PG8_LDB(dst, b, h) do { _Pragma("unroll") for (int n = 0; n < 2; ++n) _Pragma("unroll") for (int k = 0; k < 2; ++k) dst[n][k] = *(const PG8_LAS bf16x8*)(lds + PG8_SB(b, h) + boff + n * 2048 + k * 1024); } while (0)
; #define PG8_MMA(ai, bj, At, Bt) do { __builtin_amdgcn_s_setprio(1); _Pragma("unroll") for (int m = 0; m < 4; ++m) _Pragma("unroll") for (int n = 0; n < 2; ++n) _Pragma("unroll") for (int k = 0; k < 2; ++k) \
;         acc[ai][bj][m][n] = mma16<Epi::I8>(Bt[n][k], At[m][k], acc[ai][bj][m][n]); __builtin_amdgcn_s_setprio(0); } while (0)
; #define PG8_WAIT_V(n) asm volatile("s_waitcnt vmcnt(" #n ")" ::: "memory")
; #define PG8_WAIT_L(n) asm volatile("s_waitcnt lgkmcnt(" #n ")" ::: "memory")
; #define PG8_BAR __builtin_amdgcn_s_barrier()
; #define PG8_SCHED __builtin_amdgcn_sched_barrier(0)
; template <class Epi, class Sched, bool ALIGN_EPI = false, bool SP2 = false>
; __device__ __forceinline__ void gemm_phase(PG8_LAS unsigned char* lds, const Gemm g, const Sched& S, const Epi& E) {
;     ...
;             PG8_WAIT_V(8); PG8_WAIT_L(0); PG8_BAR; PG8_MMA(1, 0, At, B0); PG8_MMA(1, 1, At, B1); PG8_BAR; PG8_SCHED;
;             PG8_LDB(B0, 1, 0); PG8_LDB(B1, 1, 1); PG8_SCHED; PG8_LDA(At, 1, 0); PG8_STAGE(PG8_SA(0, 1), a2 + hstep, voffA);
;             PG8_WAIT_V(8); PG8_WAIT_L(0); PG8_BAR; PG8_MMA(0, 0, At, B0); PG8_MMA(0, 1, At, B1); PG8_BAR; PG8_SCHED;
	s_waitcnt lgkmcnt(0)
	v_mfma_f32_16x16x32_bf16 v[62:65], v[98:101], v[162:165], 0
	v_mfma_f32_16x16x32_bf16 v[58:61], v[114:117], v[162:165], 0
	v_mfma_f32_16x16x32_bf16 v[42:45], v[114:117], v[170:173], 0
	v_mfma_f32_16x16x32_bf16 v[46:49], v[98:101], v[170:173], 0
	v_mfma_f32_16x16x32_bf16 v[30:33], v[98:101], v[178:181], 0
	v_mfma_f32_16x16x32_bf16 v[26:29], v[114:117], v[178:181], 0
	v_mfma_f32_16x16x32_bf16 v[10:13], v[114:117], v[186:189], 0
	v_mfma_f32_16x16x32_bf16 v[14:17], v[98:101], v[186:189], 0
	v_mfma_f32_16x16x32_bf16 v[62:65], v[102:105], v[166:169], v[62:65]
	v_mfma_f32_16x16x32_bf16 v[58:61], v[122:125], v[166:169], v[58:61]
	v_mfma_f32_16x16x32_bf16 v[42:45], v[122:125], v[174:177], v[42:45]
	v_mfma_f32_16x16x32_bf16 v[46:49], v[102:105], v[174:177], v[46:49]
	v_mfma_f32_16x16x32_bf16 v[30:33], v[102:105], v[182:185], v[30:33]
	v_mfma_f32_16x16x32_bf16 v[26:29], v[122:125], v[182:185], v[26:29]
	v_mfma_f32_16x16x32_bf16 v[10:13], v[122:125], v[190:193], v[10:13]
	v_mfma_f32_16x16x32_bf16 v[14:17], v[102:105], v[190:193], v[14:17]
	v_mfma_f32_16x16x32_bf16 v[54:57], v[130:133], v[162:165], 0
	v_mfma_f32_16x16x32_bf16 v[50:53], v[146:149], v[162:165], 0
	v_mfma_f32_16x16x32_bf16 v[34:37], v[146:149], v[170:173], 0
	v_mfma_f32_16x16x32_bf16 v[38:41], v[130:133], v[170:173], 0
	v_mfma_f32_16x16x32_bf16 v[22:25], v[130:133], v[178:181], 0
	v_mfma_f32_16x16x32_bf16 v[18:21], v[146:149], v[178:181], 0
	v_mfma_f32_16x16x32_bf16 v[2:5], v[146:149], v[186:189], 0
	v_mfma_f32_16x16x32_bf16 v[6:9], v[130:133], v[186:189], 0
	v_mfma_f32_16x16x32_bf16 v[54:57], v[138:141], v[166:169], v[54:57]
	v_mfma_f32_16x16x32_bf16 v[50:53], v[154:157], v[166:169], v[50:53]
	v_mfma_f32_16x16x32_bf16 v[34:37], v[154:157], v[174:177], v[34:37]
	v_mfma_f32_16x16x32_bf16 v[38:41], v[138:141], v[174:177], v[38:41]
	v_mfma_f32_16x16x32_bf16 v[22:25], v[138:141], v[182:185], v[22:25]
	v_mfma_f32_16x16x32_bf16 v[18:21], v[154:157], v[182:185], v[18:21]
	v_mfma_f32_16x16x32_bf16 v[2:5], v[154:157], v[190:193], v[2:5]
	v_mfma_f32_16x16x32_bf16 v[6:9], v[138:141], v[190:193], v[6:9]
	s_barrier
	s_add_i32 s84, 0, 0x18000
	s_add_i32 vcc_hi, 0, 0x1c000
	v_add_u32_e32 v122, s84, v248
	v_add_u32_e32 v154, vcc_hi, v248
	ds_read_b128 v[98:101], v122
	ds_read_b128 v[102:105], v122 offset:1024
	ds_read_b128 v[114:117], v122 offset:2048
	ds_read_b128 v[122:125], v122 offset:3072
	ds_read_b128 v[130:133], v154
	ds_read_b128 v[138:141], v154 offset:1024
	ds_read_b128 v[146:149], v154 offset:2048
	ds_read_b128 v[154:157], v154 offset:3072
	s_add_u32 s4, s8, s100
	s_addc_u32 s5, s9, 0
	s_mov_b32 m0, s71
	v_lshl_add_u64 v[222:223], s[4:5], 0, v[194:195]
	ds_read_b128 v[162:165], v249 offset:32768
	ds_read_b128 v[166:169], v249 offset:33792
	ds_read_b128 v[170:173], v249 offset:34816
	ds_read_b128 v[174:177], v249 offset:35840
	ds_read_b128 v[178:181], v249 offset:36864
	ds_read_b128 v[182:185], v249 offset:37888
	ds_read_b128 v[186:189], v249 offset:38912
	ds_read_b128 v[190:193], v249 offset:39936
	global_load_lds_dwordx4 v[222:223], off
	v_lshl_add_u64 v[222:223], s[4:5], 0, v[196:197]
	s_mov_b32 m0, s12
	s_nop 0
	global_load_lds_dwordx4 v[222:223], off
	s_waitcnt vmcnt(8)
	s_waitcnt lgkmcnt(0)
	s_barrier
	s_waitcnt lgkmcnt(0)
	v_mfma_f32_16x16x32_bf16 v[158:161], v[98:101], v[162:165], v[158:161]
	v_mfma_f32_16x16x32_bf16 v[150:153], v[114:117], v[162:165], v[150:153]
	v_mfma_f32_16x16x32_bf16 v[118:121], v[114:117], v[170:173], v[118:121]
	v_mfma_f32_16x16x32_bf16 v[126:129], v[98:101], v[170:173], v[126:129]
	v_mfma_f32_16x16x32_bf16 v[94:97], v[98:101], v[178:181], v[94:97]
	v_mfma_f32_16x16x32_bf16 v[90:93], v[114:117], v[178:181], v[90:93]
	v_mfma_f32_16x16x32_bf16 v[74:77], v[114:117], v[186:189], v[74:77]
	v_mfma_f32_16x16x32_bf16 v[78:81], v[98:101], v[186:189], v[78:81]
	v_mfma_f32_16x16x32_bf16 v[158:161], v[102:105], v[166:169], v[158:161]
	v_mfma_f32_16x16x32_bf16 v[150:153], v[122:125], v[166:169], v[150:153]
	v_mfma_f32_16x16x32_bf16 v[118:121], v[122:125], v[174:177], v[118:121]
	v_mfma_f32_16x16x32_bf16 v[126:129], v[102:105], v[174:177], v[126:129]
	v_mfma_f32_16x16x32_bf16 v[94:97], v[102:105], v[182:185], v[94:97]
	v_mfma_f32_16x16x32_bf16 v[90:93], v[122:125], v[182:185], v[90:93]
	v_mfma_f32_16x16x32_bf16 v[74:77], v[122:125], v[190:193], v[74:77]
	v_mfma_f32_16x16x32_bf16 v[78:81], v[102:105], v[190:193], v[78:81]
	v_mfma_f32_16x16x32_bf16 v[142:145], v[130:133], v[162:165], v[142:145]
	v_mfma_f32_16x16x32_bf16 v[134:137], v[146:149], v[162:165], v[134:137]
	v_mfma_f32_16x16x32_bf16 v[106:109], v[146:149], v[170:173], v[106:109]
	v_mfma_f32_16x16x32_bf16 v[110:113], v[130:133], v[170:173], v[110:113]
	v_mfma_f32_16x16x32_bf16 v[86:89], v[130:133], v[178:181], v[86:89]
	v_mfma_f32_16x16x32_bf16 v[82:85], v[146:149], v[178:181], v[82:85]
	v_mfma_f32_16x16x32_bf16 v[66:69], v[146:149], v[186:189], v[66:69]
	v_mfma_f32_16x16x32_bf16 v[70:73], v[130:133], v[186:189], v[70:73]
	v_mfma_f32_16x16x32_bf16 v[142:145], v[138:141], v[166:169], v[142:145]
	v_mfma_f32_16x16x32_bf16 v[134:137], v[154:157], v[166:169], v[134:137]
	v_mfma_f32_16x16x32_bf16 v[106:109], v[154:157], v[174:177], v[106:109]
	v_mfma_f32_16x16x32_bf16 v[110:113], v[138:141], v[174:177], v[110:113]
	v_mfma_f32_16x16x32_bf16 v[86:89], v[138:141], v[182:185], v[86:89]
	v_mfma_f32_16x16x32_bf16 v[82:85], v[154:157], v[182:185], v[82:85]
	v_mfma_f32_16x16x32_bf16 v[66:69], v[154:157], v[190:193], v[66:69]
	v_mfma_f32_16x16x32_bf16 v[70:73], v[138:141], v[190:193], v[70:73]
	s_barrier
; #define PG8_STAGE(bufoff, gbase, voff) do { _Pragma("unroll") for (int _i = 0; _i < 2; ++_i) \
;         __builtin_amdgcn_global_load_lds((const unsigned*)((const char*)(gbase) + (voff)[_i]), (PG8_LAS unsigned*)(lds + (bufoff) + ldsw + _i * 8192), 16, 0, 0); } while (0)
; #define PG8_LDA(dst, b, h) do { _Pragma("unroll") for (int m = 0; m < 4; ++m) _Pragma("unroll") for (int k = 0; k < 2; ++k) dst[m][k] = *(const PG8_LAS bf16x8*)(lds + PG8_SA(b, h) + aoff + m * 2048 + k * 1024); } while (0)
; #define PG8_MMA(ai, bj, At, Bt) do { __builtin_amdgcn_s_setprio(1); _Pragma("unroll") for (int m = 0; m < 4; ++m) _Pragma("unroll") for (int n = 0; n < 2; ++n) _Pragma("unroll") for (int k = 0; k < 2; ++k) \
;         acc[ai][bj][m][n] = mma16<Epi::I8>(Bt[n][k], At[m][k], acc[ai][bj][m][n]); __builtin_amdgcn_s_setprio(0); } while (0)
; #define PG8_WAIT_V(n) asm volatile("s_waitcnt vmcnt(" #n ")" ::: "memory")
; #define PG8_WAIT_L(n) asm volatile("s_waitcnt lgkmcnt(" #n ")" ::: "memory")
; #define PG8_BAR __builtin_amdgcn_s_barrier()
; #define PG8_SCHED __builtin_amdgcn_sched_barrier(0)
; template <class Epi, class Sched, bool ALIGN_EPI = false, bool SP2 = false>
; __device__ __forceinline__ void gemm_phase(PG8_LAS unsigned char* lds, const Gemm g, const Sched& S, const Epi& E) {
;     ...
;             PG8_LDA(At, 1, 1); PG8_STAGE(PG8_SB(1, 0), b3, voffB); PG8_STAGE(PG8_SB(1, 1), b3 + hstep, voffB); PG8_STAGE(PG8_SA(1, 0), a3, voffA);
;             PG8_WAIT_V(8); PG8_WAIT_L(0); PG8_BAR; PG8_MMA(1, 0, At, B0); PG8_MMA(1, 1, At, B1); PG8_BAR; PG8_SCHED;
	s_add_i32 s4, s84, s80
	v_lshl_add_u64 v[206:207], v[206:207], 0, s[98:99]
	s_mov_b32 m0, s4
	ds_read_b128 v[162:165], v249 offset:49152
	ds_read_b128 v[166:169], v249 offset:50176
	ds_read_b128 v[170:173], v249 offset:51200
	ds_read_b128 v[174:177], v249 offset:52224
	ds_read_b128 v[178:181], v249 offset:53248
	ds_read_b128 v[182:185], v249 offset:54272
	ds_read_b128 v[186:189], v249 offset:55296
	ds_read_b128 v[190:193], v249 offset:56320
	global_load_lds_dwordx4 v[206:207], off
	v_lshl_add_u64 v[206:207], v[212:213], 0, s[98:99]
	s_add_i32 m0, s4, 0x2000
	s_add_i32 s4, vcc_hi, s80
	global_load_lds_dwordx4 v[206:207], off
	v_lshl_add_u64 v[206:207], v[214:215], 0, s[98:99]
	s_mov_b32 m0, s4
	s_nop 0
	global_load_lds_dwordx4 v[206:207], off
	v_lshl_add_u64 v[206:207], v[216:217], 0, s[98:99]
	s_add_i32 m0, s4, 0x2000
	s_nop 0
	global_load_lds_dwordx4 v[206:207], off
	v_lshl_add_u64 v[206:207], v[218:219], 0, s[98:99]
	s_mov_b32 m0, s10
	s_nop 0
	global_load_lds_dwordx4 v[206:207], off
	v_lshl_add_u64 v[206:207], v[220:221], 0, s[98:99]
	s_mov_b32 m0, s11
	s_nop 0
	global_load_lds_dwordx4 v[206:207], off
	s_waitcnt vmcnt(8)
	s_waitcnt lgkmcnt(0)
	s_barrier
	s_waitcnt lgkmcnt(0)
	v_mfma_f32_16x16x32_bf16 v[62:65], v[98:101], v[162:165], v[62:65]
	v_mfma_f32_16x16x32_bf16 v[58:61], v[114:117], v[162:165], v[58:61]
	v_mfma_f32_16x16x32_bf16 v[42:45], v[114:117], v[170:173], v[42:45]
	v_mfma_f32_16x16x32_bf16 v[46:49], v[98:101], v[170:173], v[46:49]
	v_mfma_f32_16x16x32_bf16 v[30:33], v[98:101], v[178:181], v[30:33]
	v_mfma_f32_16x16x32_bf16 v[26:29], v[114:117], v[178:181], v[26:29]
	v_mfma_f32_16x16x32_bf16 v[10:13], v[114:117], v[186:189], v[10:13]
	v_mfma_f32_16x16x32_bf16 v[14:17], v[98:101], v[186:189], v[14:17]
	v_mfma_f32_16x16x32_bf16 v[62:65], v[102:105], v[166:169], v[62:65]
	v_mfma_f32_16x16x32_bf16 v[58:61], v[122:125], v[166:169], v[58:61]
	v_mfma_f32_16x16x32_bf16 v[42:45], v[122:125], v[174:177], v[42:45]
	v_mfma_f32_16x16x32_bf16 v[46:49], v[102:105], v[174:177], v[46:49]
	v_mfma_f32_16x16x32_bf16 v[30:33], v[102:105], v[182:185], v[30:33]
	v_mfma_f32_16x16x32_bf16 v[26:29], v[122:125], v[182:185], v[26:29]
	v_mfma_f32_16x16x32_bf16 v[10:13], v[122:125], v[190:193], v[10:13]
	v_mfma_f32_16x16x32_bf16 v[14:17], v[102:105], v[190:193], v[14:17]
	v_mfma_f32_16x16x32_bf16 v[54:57], v[130:133], v[162:165], v[54:57]
	v_mfma_f32_16x16x32_bf16 v[50:53], v[146:149], v[162:165], v[50:53]
	v_mfma_f32_16x16x32_bf16 v[34:37], v[146:149], v[170:173], v[34:37]
	v_mfma_f32_16x16x32_bf16 v[38:41], v[130:133], v[170:173], v[38:41]
	v_mfma_f32_16x16x32_bf16 v[22:25], v[130:133], v[178:181], v[22:25]
	v_mfma_f32_16x16x32_bf16 v[18:21], v[146:149], v[178:181], v[18:21]
	v_mfma_f32_16x16x32_bf16 v[2:5], v[146:149], v[186:189], v[2:5]
	v_mfma_f32_16x16x32_bf16 v[6:9], v[130:133], v[186:189], v[6:9]
	v_mfma_f32_16x16x32_bf16 v[54:57], v[138:141], v[166:169], v[54:57]
	v_mfma_f32_16x16x32_bf16 v[50:53], v[154:157], v[166:169], v[50:53]
	v_mfma_f32_16x16x32_bf16 v[34:37], v[154:157], v[174:177], v[34:37]
	v_mfma_f32_16x16x32_bf16 v[38:41], v[138:141], v[174:177], v[38:41]
	v_mfma_f32_16x16x32_bf16 v[22:25], v[138:141], v[182:185], v[22:25]
	v_mfma_f32_16x16x32_bf16 v[18:21], v[154:157], v[182:185], v[18:21]
	v_mfma_f32_16x16x32_bf16 v[2:5], v[154:157], v[190:193], v[2:5]
	v_mfma_f32_16x16x32_bf16 v[6:9], v[138:141], v[190:193], v[6:9]
	s_barrier
	s_add_u32 s6, s6, s98
	s_addc_u32 s7, s7, 0
	s_add_u32 s6, s6, s98
	s_addc_u32 s7, s7, 0
	s_add_u32 s67, s67, s98
	s_addc_u32 s85, s85, 0
	s_add_u32 s67, s67, s98
	s_addc_u32 s85, s85, 0
	s_cmp_ge_u32 vcc_lo, s69
	s_mov_b32 s8, vcc_lo
	s_cbranch_scc0 .LBB0_175
	s_branch .Lpeelx175
	.p2align	6

; #define PG8_STAGE(bufoff, gbase, voff) do { _Pragma("unroll") for (int _i = 0; _i < 2; ++_i) \
;         __builtin_amdgcn_global_load_lds((const unsigned*)((const char*)(gbase) + (voff)[_i]), (PG8_LAS unsigned*)(lds + (bufoff) + ldsw + _i * 8192), 16, 0, 0); } while (0)
; #define PG8_LDA(dst, b, h) do { _Pragma("unroll") for (int m = 0; m < 4; ++m) _Pragma("unroll") for (int k = 0; k < 2; ++k) dst[m][k] = *(const PG8_LAS bf16x8*)(lds + PG8_SA(b, h) + aoff + m * 2048 + k * 1024); } while (0)
; #define PG8_LDB(dst, b, h) do { _Pragma("unroll") for (int n = 0; n < 2; ++n) _Pragma("unroll") for (int k = 0; k < 2; ++k) dst[n][k] = *(const PG8_LAS bf16x8*)(lds + PG8_SB(b, h) + boff + n * 2048 + k * 1024); } while (0)
; #define PG8_MMA(ai, bj, At, Bt) do { __builtin_amdgcn_s_setprio(1); _Pragma("unroll") for (int m = 0; m < 4; ++m) _Pragma("unroll") for (int n = 0; n < 2; ++n) _Pragma("unroll") for (int k = 0; k < 2; ++k) \
;         acc[ai][bj][m][n] = mma16<Epi::I8>(Bt[n][k], At[m][k], acc[ai][bj][m][n]); __builtin_amdgcn_s_setprio(0); } while (0)
; #define PG8_WAIT_V(n) asm volatile("s_waitcnt vmcnt(" #n ")" ::: "memory")
; #define PG8_WAIT_L(n) asm volatile("s_waitcnt lgkmcnt(" #n ")" ::: "memory")
; #define PG8_BAR __builtin_amdgcn_s_barrier()
; template <class Epi, class Sched, bool ALIGN_EPI = false, bool SP2 = false>
; __device__ __forceinline__ void gemm_phase(PG8_LAS unsigned char* lds, const Gemm g, const Sched& S, const Epi& E) {
;     ...
;             const bool last = (t == nt - 2);
;             const char* a1 = cA + (size_t)(t + 1) * kstep;
;             const char* a2 = last ? nA : cA + (size_t)(t + 2) * kstep; const char* b2 = last ? nB : cB + (size_t)(t + 2) * kstep;
;             const char* a3 = a2 + kstep; const char* b3 = b2 + kstep;
;             if (last && has_next) S.a_ready(nxt);
;             if constexpr (SP2) {
;             PG8_LDB(B0, 0, 0); PG8_LDB(B1, 0, 1); PG8_SCHED; PG8_LDA(At, 0, 0); PG8_STAGE(PG8_SA(1, 1), a1 + hstep, voffA);
;             PG8_WAIT_V(8); PG8_WAIT_L(0); PG8_BAR; PG8_MMA(0, 0, At, B0); PG8_MMA(0, 1, At, B1); PG8_BAR; PG8_SCHED;
;             PG8_LDA(At, 0, 1); PG8_STAGE(PG8_SB(0, 0), b2, voffB); PG8_STAGE(PG8_SB(0, 1), b2 + hstep, voffB); PG8_STAGE(PG8_SA(0, 0), a2, voffA);
;             PG8_WAIT_V(8); PG8_WAIT_L(0); PG8_BAR; PG8_MMA(1, 0, At, B0); PG8_MMA(1, 1, At, B1); PG8_BAR; PG8_SCHED;
.Lpeel291:
	s_add_u32 s84, s8, 0x100
	s_addc_u32 s85, s9, 0
	s_add_i32 s66, 0, 0x10000
	s_cmp_eq_u32 s10, 12
	s_cselect_b32 vcc_hi, s5, s85
	s_cselect_b32 vcc_lo, s7, s84
	s_cselect_b32 s97, s11, s68
	s_cselect_b32 s96, s67, s69
	s_add_i32 s70, 0, 0x14000
	v_add_u32_e32 v110, s66, v175
	v_add_u32_e32 v168, s70, v175
	s_waitcnt vmcnt(0)
	ds_read_b128 v[66:69], v110
	ds_read_b128 v[70:73], v110 offset:1024
	ds_read_b128 v[106:109], v110 offset:2048
	ds_read_b128 v[110:113], v110 offset:3072
	ds_read_b128 v[114:117], v168
	ds_read_b128 v[118:121], v168 offset:1024
	ds_read_b128 v[126:129], v168 offset:2048
	ds_read_b128 v[178:181], v168 offset:3072
	v_lshl_add_u64 v[168:169], s[8:9], 0, v[164:165]
	s_add_i32 m0, s1, 0xc000
	ds_read_b128 v[182:185], v177
	ds_read_b128 v[186:189], v177 offset:1024
	ds_read_b128 v[190:193], v177 offset:2048
	ds_read_b128 v[194:197], v177 offset:3072
	ds_read_b128 v[198:201], v177 offset:4096
	ds_read_b128 v[210:213], v177 offset:5120
	ds_read_b128 v[214:217], v177 offset:6144
	ds_read_b128 v[218:221], v177 offset:7168
	global_load_lds_dwordx4 v[168:169], off
	v_lshl_add_u64 v[168:169], s[8:9], 0, v[166:167]
	s_add_i32 m0, s1, 0xe000
	s_nop 0
	global_load_lds_dwordx4 v[168:169], off
	s_waitcnt vmcnt(8)
	s_waitcnt lgkmcnt(0)
	s_barrier
	s_waitcnt lgkmcnt(0)
	v_mfma_i32_16x16x64_i8 v[154:157], v[66:69], v[182:185], 0
	v_mfma_i32_16x16x64_i8 v[146:149], v[106:109], v[182:185], 0
	v_mfma_i32_16x16x64_i8 v[138:141], v[106:109], v[190:193], 0
	v_mfma_i32_16x16x64_i8 v[150:153], v[66:69], v[190:193], 0
	v_mfma_i32_16x16x64_i8 v[142:145], v[66:69], v[198:201], 0
	v_mfma_i32_16x16x64_i8 v[130:133], v[106:109], v[198:201], 0
	v_mfma_i32_16x16x64_i8 v[122:125], v[106:109], v[214:217], 0
	v_mfma_i32_16x16x64_i8 v[134:137], v[66:69], v[214:217], 0
	v_mfma_i32_16x16x64_i8 v[154:157], v[70:73], v[186:189], v[154:157]
	v_mfma_i32_16x16x64_i8 v[146:149], v[110:113], v[186:189], v[146:149]
	v_mfma_i32_16x16x64_i8 v[138:141], v[110:113], v[194:197], v[138:141]
	v_mfma_i32_16x16x64_i8 v[150:153], v[70:73], v[194:197], v[150:153]
	v_mfma_i32_16x16x64_i8 v[142:145], v[70:73], v[210:213], v[142:145]
	v_mfma_i32_16x16x64_i8 v[130:133], v[110:113], v[210:213], v[130:133]
	v_mfma_i32_16x16x64_i8 v[122:125], v[110:113], v[218:221], v[122:125]
	v_mfma_i32_16x16x64_i8 v[134:137], v[70:73], v[218:221], v[134:137]
	v_mfma_i32_16x16x64_i8 v[102:105], v[114:117], v[182:185], 0
	v_mfma_i32_16x16x64_i8 v[94:97], v[126:129], v[182:185], 0
	v_mfma_i32_16x16x64_i8 v[86:89], v[126:129], v[190:193], 0
	v_mfma_i32_16x16x64_i8 v[98:101], v[114:117], v[190:193], 0
	v_mfma_i32_16x16x64_i8 v[90:93], v[114:117], v[198:201], 0
	v_mfma_i32_16x16x64_i8 v[78:81], v[126:129], v[198:201], 0
	v_mfma_i32_16x16x64_i8 v[74:77], v[126:129], v[214:217], 0
	v_mfma_i32_16x16x64_i8 v[82:85], v[114:117], v[214:217], 0
	v_mfma_i32_16x16x64_i8 v[102:105], v[118:121], v[186:189], v[102:105]
	v_mfma_i32_16x16x64_i8 v[94:97], v[178:181], v[186:189], v[94:97]
	v_mfma_i32_16x16x64_i8 v[86:89], v[178:181], v[194:197], v[86:89]
	v_mfma_i32_16x16x64_i8 v[98:101], v[118:121], v[194:197], v[98:101]
	v_mfma_i32_16x16x64_i8 v[90:93], v[118:121], v[210:213], v[90:93]
	v_mfma_i32_16x16x64_i8 v[78:81], v[178:181], v[210:213], v[78:81]
	v_mfma_i32_16x16x64_i8 v[74:77], v[178:181], v[218:221], v[74:77]
	v_mfma_i32_16x16x64_i8 v[82:85], v[118:121], v[218:221], v[82:85]
	s_barrier
	s_add_i32 s8, s66, s81
	v_lshl_add_u64 v[168:169], s[96:97], 0, v[0:1]
	s_mov_b32 m0, s8
	ds_read_b128 v[182:185], v177 offset:16384
	ds_read_b128 v[186:189], v177 offset:17408
	ds_read_b128 v[190:193], v177 offset:18432
	ds_read_b128 v[194:197], v177 offset:19456
	ds_read_b128 v[198:201], v177 offset:20480
	ds_read_b128 v[210:213], v177 offset:21504
	ds_read_b128 v[214:217], v177 offset:22528
	ds_read_b128 v[218:221], v177 offset:23552
	global_load_lds_dwordx4 v[168:169], off
	s_add_i32 m0, s8, 0x2000
	s_add_u32 s8, s96, 0x40000
	v_lshl_add_u64 v[206:207], s[96:97], 0, v[158:159]
	s_addc_u32 s9, s97, 0
	s_add_i32 s66, s70, s81
	global_load_lds_dwordx4 v[206:207], off
	v_lshl_add_u64 v[222:223], s[8:9], 0, v[0:1]
	s_mov_b32 m0, s66
	v_lshl_add_u64 v[224:225], vcc, 0, v[160:161]
	global_load_lds_dwordx4 v[222:223], off
	v_lshl_add_u64 v[222:223], s[8:9], 0, v[158:159]
	s_add_i32 m0, s66, 0x2000
	s_nop 0
	global_load_lds_dwordx4 v[222:223], off
	v_lshl_add_u64 v[222:223], vcc, 0, v[162:163]
	s_mov_b32 m0, s1
	s_nop 0
	global_load_lds_dwordx4 v[222:223], off
	s_mov_b32 m0, s58
	s_nop 0
	global_load_lds_dwordx4 v[224:225], off
	s_waitcnt vmcnt(8)
	s_waitcnt lgkmcnt(0)
	s_barrier
	s_waitcnt lgkmcnt(0)
	v_mfma_i32_16x16x64_i8 v[62:65], v[66:69], v[182:185], 0
	v_mfma_i32_16x16x64_i8 v[54:57], v[106:109], v[182:185], 0
	v_mfma_i32_16x16x64_i8 v[46:49], v[106:109], v[190:193], 0
	v_mfma_i32_16x16x64_i8 v[58:61], v[66:69], v[190:193], 0
	v_mfma_i32_16x16x64_i8 v[50:53], v[66:69], v[198:201], 0
	v_mfma_i32_16x16x64_i8 v[38:41], v[106:109], v[198:201], 0
	v_mfma_i32_16x16x64_i8 v[34:37], v[106:109], v[214:217], 0
	v_mfma_i32_16x16x64_i8 v[42:45], v[66:69], v[214:217], 0
	v_mfma_i32_16x16x64_i8 v[62:65], v[70:73], v[186:189], v[62:65]
	v_mfma_i32_16x16x64_i8 v[54:57], v[110:113], v[186:189], v[54:57]
	v_mfma_i32_16x16x64_i8 v[46:49], v[110:113], v[194:197], v[46:49]
	v_mfma_i32_16x16x64_i8 v[58:61], v[70:73], v[194:197], v[58:61]
	v_mfma_i32_16x16x64_i8 v[50:53], v[70:73], v[210:213], v[50:53]
	v_mfma_i32_16x16x64_i8 v[38:41], v[110:113], v[210:213], v[38:41]
	v_mfma_i32_16x16x64_i8 v[34:37], v[110:113], v[218:221], v[34:37]
	v_mfma_i32_16x16x64_i8 v[42:45], v[70:73], v[218:221], v[42:45]
	v_mfma_i32_16x16x64_i8 v[30:33], v[114:117], v[182:185], 0
	v_mfma_i32_16x16x64_i8 v[22:25], v[126:129], v[182:185], 0
	v_mfma_i32_16x16x64_i8 v[14:17], v[126:129], v[190:193], 0
	v_mfma_i32_16x16x64_i8 v[26:29], v[114:117], v[190:193], 0
	v_mfma_i32_16x16x64_i8 v[18:21], v[114:117], v[198:201], 0
	v_mfma_i32_16x16x64_i8 v[6:9], v[126:129], v[198:201], 0
	v_mfma_i32_16x16x64_i8 v[2:5], v[126:129], v[214:217], 0
	v_mfma_i32_16x16x64_i8 v[10:13], v[114:117], v[214:217], 0
	v_mfma_i32_16x16x64_i8 v[30:33], v[118:121], v[186:189], v[30:33]
	v_mfma_i32_16x16x64_i8 v[22:25], v[178:181], v[186:189], v[22:25]
	v_mfma_i32_16x16x64_i8 v[14:17], v[178:181], v[194:197], v[14:17]
	v_mfma_i32_16x16x64_i8 v[26:29], v[118:121], v[194:197], v[26:29]
	v_mfma_i32_16x16x64_i8 v[18:21], v[118:121], v[210:213], v[18:21]
	v_mfma_i32_16x16x64_i8 v[6:9], v[178:181], v[210:213], v[6:9]
	v_mfma_i32_16x16x64_i8 v[2:5], v[178:181], v[218:221], v[2:5]
	v_mfma_i32_16x16x64_i8 v[10:13], v[118:121], v[218:221], v[10:13]
	s_barrier
; #define PG8_STAGE(bufoff, gbase, voff) do { _Pragma("unroll") for (int _i = 0; _i < 2; ++_i) \
;         __builtin_amdgcn_global_load_lds((const unsigned*)((const char*)(gbase) + (voff)[_i]), (PG8_LAS unsigned*)(lds + (bufoff) + ldsw + _i * 8192), 16, 0, 0); } while (0)
; #define PG8_LDA(dst, b, h) do { _Pragma("unroll") for (int m = 0; m < 4; ++m) _Pragma("unroll") for (int k = 0; k < 2; ++k) dst[m][k] = *(const PG8_LAS bf16x8*)(lds + PG8_SA(b, h) + aoff + m * 2048 + k * 1024); } while (0)
; #define PG8_LDB(dst, b, h) do { _Pragma("unroll") for (int n = 0; n < 2; ++n) _Pragma("unroll") for (int k = 0; k < 2; ++k) dst[n][k] = *(const PG8_LAS bf16x8*)(lds + PG8_SB(b, h) + boff + n * 2048 + k * 1024); } while (0)
; #define PG8_MMA(ai, bj, At, Bt) do { __builtin_amdgcn_s_setprio(1); _Pragma("unroll") for (int m = 0; m < 4; ++m) _Pragma("unroll") for (int n = 0; n < 2; ++n) _Pragma("unroll") for (int k = 0; k < 2; ++k) \
;         acc[ai][bj][m][n] = mma16<Epi::I8>(Bt[n][k], At[m][k], acc[ai][bj][m][n]); __builtin_amdgcn_s_setprio(0); } while (0)
; #define PG8_WAIT_V(n) asm volatile("s_waitcnt vmcnt(" #n ")" ::: "memory")
; #define PG8_WAIT_L(n) asm volatile("s_waitcnt lgkmcnt(" #n ")" ::: "memory")
; #define PG8_BAR __builtin_amdgcn_s_barrier()
; #define PG8_SCHED __builtin_amdgcn_sched_barrier(0)
; template <class Epi, class Sched, bool ALIGN_EPI = false, bool SP2 = false>
; __device__ __forceinline__ void gemm_phase(PG8_LAS unsigned char* lds, const Gemm g, const Sched& S, const Epi& E) {
;     ...
;             PG8_LDB(B0, 1, 0); PG8_LDB(B1, 1, 1); PG8_SCHED; PG8_LDA(At, 1, 0); PG8_STAGE(PG8_SA(0, 1), a2 + hstep, voffA);
;             PG8_WAIT_V(8); PG8_WAIT_L(0); PG8_BAR; PG8_MMA(0, 0, At, B0); PG8_MMA(0, 1, At, B1); PG8_BAR; PG8_SCHED;
;             PG8_LDA(At, 1, 1); PG8_STAGE(PG8_SB(1, 0), b3, voffB); PG8_STAGE(PG8_SB(1, 1), b3 + hstep, voffB); PG8_STAGE(PG8_SA(1, 0), a3, voffA);
;             PG8_WAIT_V(8); PG8_WAIT_L(0); PG8_BAR; PG8_MMA(1, 0, At, B0); PG8_MMA(1, 1, At, B1); PG8_BAR; PG8_SCHED;
	s_add_i32 s66, 0, 0x18000
	s_add_i32 s70, 0, 0x1c000
	v_add_u32_e32 v110, s66, v175
	v_add_u32_e32 v170, s70, v175
	ds_read_b128 v[66:69], v110
	ds_read_b128 v[70:73], v110 offset:1024
	ds_read_b128 v[106:109], v110 offset:2048
	ds_read_b128 v[110:113], v110 offset:3072
	ds_read_b128 v[114:117], v170
	ds_read_b128 v[118:121], v170 offset:1024
	ds_read_b128 v[126:129], v170 offset:2048
	ds_read_b128 v[178:181], v170 offset:3072
	s_add_u32 s8, vcc_lo, 0x40000
	s_addc_u32 s9, vcc_hi, 0
	s_mov_b32 m0, s80
	v_lshl_add_u64 v[226:227], s[8:9], 0, v[162:163]
	ds_read_b128 v[182:185], v177 offset:32768
	ds_read_b128 v[186:189], v177 offset:33792
	ds_read_b128 v[190:193], v177 offset:34816
	ds_read_b128 v[194:197], v177 offset:35840
	ds_read_b128 v[198:201], v177 offset:36864
	ds_read_b128 v[210:213], v177 offset:37888
	ds_read_b128 v[214:217], v177 offset:38912
	ds_read_b128 v[218:221], v177 offset:39936
	global_load_lds_dwordx4 v[226:227], off
	v_lshl_add_u64 v[226:227], s[8:9], 0, v[160:161]
	s_mov_b32 m0, s0
	s_nop 0
	global_load_lds_dwordx4 v[226:227], off
	s_waitcnt vmcnt(8)
	s_waitcnt lgkmcnt(0)
	s_barrier
	s_waitcnt lgkmcnt(0)
	v_mfma_i32_16x16x64_i8 v[154:157], v[66:69], v[182:185], v[154:157]
	v_mfma_i32_16x16x64_i8 v[146:149], v[106:109], v[182:185], v[146:149]
	v_mfma_i32_16x16x64_i8 v[138:141], v[106:109], v[190:193], v[138:141]
	v_mfma_i32_16x16x64_i8 v[150:153], v[66:69], v[190:193], v[150:153]
	v_mfma_i32_16x16x64_i8 v[142:145], v[66:69], v[198:201], v[142:145]
	v_mfma_i32_16x16x64_i8 v[130:133], v[106:109], v[198:201], v[130:133]
	v_mfma_i32_16x16x64_i8 v[122:125], v[106:109], v[214:217], v[122:125]
	v_mfma_i32_16x16x64_i8 v[134:137], v[66:69], v[214:217], v[134:137]
	v_mfma_i32_16x16x64_i8 v[154:157], v[70:73], v[186:189], v[154:157]
	v_mfma_i32_16x16x64_i8 v[146:149], v[110:113], v[186:189], v[146:149]
	v_mfma_i32_16x16x64_i8 v[138:141], v[110:113], v[194:197], v[138:141]
	v_mfma_i32_16x16x64_i8 v[150:153], v[70:73], v[194:197], v[150:153]
	v_mfma_i32_16x16x64_i8 v[142:145], v[70:73], v[210:213], v[142:145]
	v_mfma_i32_16x16x64_i8 v[130:133], v[110:113], v[210:213], v[130:133]
	v_mfma_i32_16x16x64_i8 v[122:125], v[110:113], v[218:221], v[122:125]
	v_mfma_i32_16x16x64_i8 v[134:137], v[70:73], v[218:221], v[134:137]
	v_mfma_i32_16x16x64_i8 v[102:105], v[114:117], v[182:185], v[102:105]
	v_mfma_i32_16x16x64_i8 v[94:97], v[126:129], v[182:185], v[94:97]
	v_mfma_i32_16x16x64_i8 v[86:89], v[126:129], v[190:193], v[86:89]
	v_mfma_i32_16x16x64_i8 v[98:101], v[114:117], v[190:193], v[98:101]
	v_mfma_i32_16x16x64_i8 v[90:93], v[114:117], v[198:201], v[90:93]
	v_mfma_i32_16x16x64_i8 v[78:81], v[126:129], v[198:201], v[78:81]
	v_mfma_i32_16x16x64_i8 v[74:77], v[126:129], v[214:217], v[74:77]
	v_mfma_i32_16x16x64_i8 v[82:85], v[114:117], v[214:217], v[82:85]
	v_mfma_i32_16x16x64_i8 v[102:105], v[118:121], v[186:189], v[102:105]
	v_mfma_i32_16x16x64_i8 v[94:97], v[178:181], v[186:189], v[94:97]
	v_mfma_i32_16x16x64_i8 v[86:89], v[178:181], v[194:197], v[86:89]
	v_mfma_i32_16x16x64_i8 v[98:101], v[118:121], v[194:197], v[98:101]
	v_mfma_i32_16x16x64_i8 v[90:93], v[118:121], v[210:213], v[90:93]
	v_mfma_i32_16x16x64_i8 v[78:81], v[178:181], v[210:213], v[78:81]
	v_mfma_i32_16x16x64_i8 v[74:77], v[178:181], v[218:221], v[74:77]
	v_mfma_i32_16x16x64_i8 v[82:85], v[118:121], v[218:221], v[82:85]
	s_barrier
	s_add_i32 s8, s66, s81
	v_lshl_add_u64 v[168:169], v[168:169], 0, s[92:93]
	s_mov_b32 m0, s8
	ds_read_b128 v[182:185], v177 offset:49152
	ds_read_b128 v[186:189], v177 offset:50176
	ds_read_b128 v[190:193], v177 offset:51200
	ds_read_b128 v[194:197], v177 offset:52224
	ds_read_b128 v[198:201], v177 offset:53248
	ds_read_b128 v[210:213], v177 offset:54272
	ds_read_b128 v[214:217], v177 offset:55296
	ds_read_b128 v[218:221], v177 offset:56320
	global_load_lds_dwordx4 v[168:169], off
	s_add_i32 m0, s8, 0x2000
	s_add_u32 s8, s96, 0x40080
	v_lshl_add_u64 v[168:169], v[206:207], 0, s[92:93]
	s_addc_u32 s9, s97, 0
	s_add_i32 s66, s70, s81
	global_load_lds_dwordx4 v[168:169], off
	v_lshl_add_u64 v[168:169], s[8:9], 0, v[0:1]
	s_mov_b32 m0, s66
	s_nop 0
	global_load_lds_dwordx4 v[168:169], off
	v_lshl_add_u64 v[168:169], s[8:9], 0, v[158:159]
	s_add_i32 m0, s66, 0x2000
	s_nop 0
	global_load_lds_dwordx4 v[168:169], off
	v_lshl_add_u64 v[168:169], v[222:223], 0, s[92:93]
	s_mov_b32 m0, s13
	s_nop 0
	global_load_lds_dwordx4 v[168:169], off
	v_lshl_add_u64 v[168:169], v[224:225], 0, s[92:93]
	s_mov_b32 m0, s12
	s_nop 0
	global_load_lds_dwordx4 v[168:169], off
	s_waitcnt vmcnt(8)
	s_waitcnt lgkmcnt(0)
	s_barrier
	s_waitcnt lgkmcnt(0)
	v_mfma_i32_16x16x64_i8 v[62:65], v[66:69], v[182:185], v[62:65]
	v_mfma_i32_16x16x64_i8 v[54:57], v[106:109], v[182:185], v[54:57]
	v_mfma_i32_16x16x64_i8 v[46:49], v[106:109], v[190:193], v[46:49]
	v_mfma_i32_16x16x64_i8 v[58:61], v[66:69], v[190:193], v[58:61]
	v_mfma_i32_16x16x64_i8 v[50:53], v[66:69], v[198:201], v[50:53]
	v_mfma_i32_16x16x64_i8 v[38:41], v[106:109], v[198:201], v[38:41]
	v_mfma_i32_16x16x64_i8 v[34:37], v[106:109], v[214:217], v[34:37]
	v_mfma_i32_16x16x64_i8 v[42:45], v[66:69], v[214:217], v[42:45]
	v_mfma_i32_16x16x64_i8 v[62:65], v[70:73], v[186:189], v[62:65]
	v_mfma_i32_16x16x64_i8 v[54:57], v[110:113], v[186:189], v[54:57]
	v_mfma_i32_16x16x64_i8 v[46:49], v[110:113], v[194:197], v[46:49]
	v_mfma_i32_16x16x64_i8 v[58:61], v[70:73], v[194:197], v[58:61]
	v_mfma_i32_16x16x64_i8 v[50:53], v[70:73], v[210:213], v[50:53]
	v_mfma_i32_16x16x64_i8 v[38:41], v[110:113], v[210:213], v[38:41]
	v_mfma_i32_16x16x64_i8 v[34:37], v[110:113], v[218:221], v[34:37]
	v_mfma_i32_16x16x64_i8 v[42:45], v[70:73], v[218:221], v[42:45]
	v_mfma_i32_16x16x64_i8 v[30:33], v[114:117], v[182:185], v[30:33]
	v_mfma_i32_16x16x64_i8 v[22:25], v[126:129], v[182:185], v[22:25]
	v_mfma_i32_16x16x64_i8 v[14:17], v[126:129], v[190:193], v[14:17]
	v_mfma_i32_16x16x64_i8 v[26:29], v[114:117], v[190:193], v[26:29]
	v_mfma_i32_16x16x64_i8 v[18:21], v[114:117], v[198:201], v[18:21]
	v_mfma_i32_16x16x64_i8 v[6:9], v[126:129], v[198:201], v[6:9]
	v_mfma_i32_16x16x64_i8 v[2:5], v[126:129], v[214:217], v[2:5]
	v_mfma_i32_16x16x64_i8 v[10:13], v[114:117], v[214:217], v[10:13]
	v_mfma_i32_16x16x64_i8 v[30:33], v[118:121], v[186:189], v[30:33]
	v_mfma_i32_16x16x64_i8 v[22:25], v[178:181], v[186:189], v[22:25]
	v_mfma_i32_16x16x64_i8 v[14:17], v[178:181], v[194:197], v[14:17]
	v_mfma_i32_16x16x64_i8 v[26:29], v[118:121], v[194:197], v[26:29]
	v_mfma_i32_16x16x64_i8 v[18:21], v[118:121], v[210:213], v[18:21]
	v_mfma_i32_16x16x64_i8 v[6:9], v[178:181], v[210:213], v[6:9]
	v_mfma_i32_16x16x64_i8 v[2:5], v[178:181], v[218:221], v[2:5]
	v_mfma_i32_16x16x64_i8 v[10:13], v[118:121], v[218:221], v[10:13]
	s_barrier
	s_add_i32 s10, s10, 2
	s_add_u32 s69, s69, 0x100
	s_addc_u32 s68, s68, 0
	s_cmp_gt_u32 s10, 13
	s_mov_b64 s[8:9], s[84:85]
	s_cbranch_scc0 .LBB0_291
	s_branch .Lpeelx291
	.p2align	6

; #define PG8_STAGE(bufoff, gbase, voff) do { _Pragma("unroll") for (int _i = 0; _i < 2; ++_i) \
;         __builtin_amdgcn_global_load_lds((const unsigned*)((const char*)(gbase) + (voff)[_i]), (PG8_LAS unsigned*)(lds + (bufoff) + ldsw + _i * 8192), 16, 0, 0); } while (0)
; #define PG8_LDA(dst, b, h) do { _Pragma("unroll") for (int m = 0; m < 4; ++m) _Pragma("unroll") for (int k = 0; k < 2; ++k) dst[m][k] = *(const PG8_LAS bf16x8*)(lds + PG8_SA(b, h) + aoff + m * 2048 + k * 1024); } while (0)
; #define PG8_LDB(dst, b, h) do { _Pragma("unroll") for (int n = 0; n < 2; ++n) _Pragma("unroll") for (int k = 0; k < 2; ++k) dst[n][k] = *(const PG8_LAS bf16x8*)(lds + PG8_SB(b, h) + boff + n * 2048 + k * 1024); } while (0)
; #define PG8_MMA(ai, bj, At, Bt) do { __builtin_amdgcn_s_setprio(1); _Pragma("unroll") for (int m = 0; m < 4; ++m) _Pragma("unroll") for (int n = 0; n < 2; ++n) _Pragma("unroll") for (int k = 0; k < 2; ++k) \
;         acc[ai][bj][m][n] = mma16<Epi::I8>(Bt[n][k], At[m][k], acc[ai][bj][m][n]); __builtin_amdgcn_s_setprio(0); } while (0)
; #define PG8_WAIT_V(n) asm volatile("s_waitcnt vmcnt(" #n ")" ::: "memory")
; #define PG8_WAIT_L(n) asm volatile("s_waitcnt lgkmcnt(" #n ")" ::: "memory")
; #define PG8_BAR __builtin_amdgcn_s_barrier()
; template <class Epi, class Sched, bool ALIGN_EPI = false, bool SP2 = false>
; __device__ __forceinline__ void gemm_phase(PG8_LAS unsigned char* lds, const Gemm g, const Sched& S, const Epi& E) {
;     ...
;             const bool last = (t == nt - 2);
;             const char* a1 = cA + (size_t)(t + 1) * kstep;
;             const char* a2 = last ? nA : cA + (size_t)(t + 2) * kstep; const char* b2 = last ? nB : cB + (size_t)(t + 2) * kstep;
;             const char* a3 = a2 + kstep; const char* b3 = b2 + kstep;
;             if (last && has_next) S.a_ready(nxt);
;             if constexpr (SP2) {
;             PG8_LDB(B0, 0, 0); PG8_LDB(B1, 0, 1); PG8_SCHED; PG8_LDA(At, 0, 0); PG8_STAGE(PG8_SA(1, 1), a1 + hstep, voffA);
;             PG8_WAIT_V(8); PG8_WAIT_L(0); PG8_BAR; PG8_MMA(0, 0, At, B0); PG8_MMA(0, 1, At, B1); PG8_BAR; PG8_SCHED;
;             PG8_LDA(At, 0, 1); PG8_STAGE(PG8_SB(0, 0), b2, voffB); PG8_STAGE(PG8_SB(0, 1), b2 + hstep, voffB); PG8_STAGE(PG8_SA(0, 0), a2, voffA);
;             PG8_WAIT_V(8); PG8_WAIT_L(0); PG8_BAR; PG8_MMA(1, 0, At, B0); PG8_MMA(1, 1, At, B1); PG8_BAR; PG8_SCHED;
.Lpeel327:
	s_add_u32 s68, s8, 0x100
	s_addc_u32 s69, s9, 0
	s_add_i32 s84, 0, 0x10000
	s_cmp_eq_u32 s4, 28
	s_cselect_b32 vcc_hi, s1, s69
	s_cselect_b32 vcc_lo, s5, s68
	v_add_u32_e32 v0, s84, v188
	s_cselect_b32 s71, s7, s96
	s_cselect_b32 s70, s85, s97
	s_add_i32 s10, 0, 0x14000
	ds_read_b128 v[52:55], v0
	ds_read_b128 v[56:59], v0 offset:1024
	ds_read_b128 v[76:79], v0 offset:2048
	ds_read_b128 v[80:83], v0 offset:3072
	v_add_u32_e32 v0, s10, v188
	ds_read_b128 v[116:119], v0
	ds_read_b128 v[120:123], v0 offset:1024
	ds_read_b128 v[168:171], v0 offset:2048
	ds_read_b128 v[172:175], v0 offset:3072
	v_lshl_add_u64 v[2:3], s[8:9], 0, v[164:165]
	s_add_i32 m0, s58, 0xc000
	ds_read_b128 v[176:179], v189
	ds_read_b128 v[180:183], v189 offset:1024
	ds_read_b128 v[190:193], v189 offset:2048
	ds_read_b128 v[194:197], v189 offset:3072
	ds_read_b128 v[198:201], v189 offset:4096
	ds_read_b128 v[210:213], v189 offset:5120
	ds_read_b128 v[214:217], v189 offset:6144
	ds_read_b128 v[218:221], v189 offset:7168
	global_load_lds_dwordx4 v[2:3], off
	v_lshl_add_u64 v[2:3], s[8:9], 0, v[166:167]
	s_add_i32 m0, s58, 0xe000
	s_nop 0
	global_load_lds_dwordx4 v[2:3], off
	s_waitcnt vmcnt(8)
	s_waitcnt lgkmcnt(0)
	s_barrier
	s_waitcnt lgkmcnt(0)
	v_mfma_f32_16x16x32_bf16 v[152:155], v[52:55], v[176:179], 0
	v_mfma_f32_16x16x32_bf16 v[144:147], v[76:79], v[176:179], 0
	v_mfma_f32_16x16x32_bf16 v[140:143], v[76:79], v[190:193], 0
	v_mfma_f32_16x16x32_bf16 v[148:151], v[52:55], v[190:193], 0
	v_mfma_f32_16x16x32_bf16 v[136:139], v[52:55], v[198:201], 0
	v_mfma_f32_16x16x32_bf16 v[132:135], v[76:79], v[198:201], 0
	v_mfma_f32_16x16x32_bf16 v[124:127], v[76:79], v[214:217], 0
	v_mfma_f32_16x16x32_bf16 v[128:131], v[52:55], v[214:217], 0
	v_mfma_f32_16x16x32_bf16 v[152:155], v[56:59], v[180:183], v[152:155]
	v_mfma_f32_16x16x32_bf16 v[144:147], v[80:83], v[180:183], v[144:147]
	v_mfma_f32_16x16x32_bf16 v[140:143], v[80:83], v[194:197], v[140:143]
	v_mfma_f32_16x16x32_bf16 v[148:151], v[56:59], v[194:197], v[148:151]
	v_mfma_f32_16x16x32_bf16 v[136:139], v[56:59], v[210:213], v[136:139]
	v_mfma_f32_16x16x32_bf16 v[132:135], v[80:83], v[210:213], v[132:135]
	v_mfma_f32_16x16x32_bf16 v[124:127], v[80:83], v[218:221], v[124:127]
	v_mfma_f32_16x16x32_bf16 v[128:131], v[56:59], v[218:221], v[128:131]
	v_mfma_f32_16x16x32_bf16 v[112:115], v[116:119], v[176:179], 0
	v_mfma_f32_16x16x32_bf16 v[104:107], v[168:171], v[176:179], 0
	v_mfma_f32_16x16x32_bf16 v[100:103], v[168:171], v[190:193], 0
	v_mfma_f32_16x16x32_bf16 v[108:111], v[116:119], v[190:193], 0
	v_mfma_f32_16x16x32_bf16 v[96:99], v[116:119], v[198:201], 0
	v_mfma_f32_16x16x32_bf16 v[92:95], v[168:171], v[198:201], 0
	v_mfma_f32_16x16x32_bf16 v[84:87], v[168:171], v[214:217], 0
	v_mfma_f32_16x16x32_bf16 v[88:91], v[116:119], v[214:217], 0
	v_mfma_f32_16x16x32_bf16 v[112:115], v[120:123], v[180:183], v[112:115]
	v_mfma_f32_16x16x32_bf16 v[104:107], v[172:175], v[180:183], v[104:107]
	v_mfma_f32_16x16x32_bf16 v[100:103], v[172:175], v[194:197], v[100:103]
	v_mfma_f32_16x16x32_bf16 v[108:111], v[120:123], v[194:197], v[108:111]
	v_mfma_f32_16x16x32_bf16 v[96:99], v[120:123], v[210:213], v[96:99]
	v_mfma_f32_16x16x32_bf16 v[92:95], v[172:175], v[210:213], v[92:95]
	v_mfma_f32_16x16x32_bf16 v[84:87], v[172:175], v[218:221], v[84:87]
	v_mfma_f32_16x16x32_bf16 v[88:91], v[120:123], v[218:221], v[88:91]
	s_barrier
	s_add_i32 s8, s84, s80
	v_lshl_add_u64 v[184:185], s[70:71], 0, v[158:159]
	s_mov_b32 m0, s8
	ds_read_b128 v[176:179], v189 offset:16384
	ds_read_b128 v[180:183], v189 offset:17408
	ds_read_b128 v[190:193], v189 offset:18432
	ds_read_b128 v[194:197], v189 offset:19456
	ds_read_b128 v[198:201], v189 offset:20480
	ds_read_b128 v[210:213], v189 offset:21504
	ds_read_b128 v[214:217], v189 offset:22528
	ds_read_b128 v[218:221], v189 offset:23552
	global_load_lds_dwordx4 v[184:185], off
	s_add_i32 m0, s8, 0x2000
	s_add_u32 s8, s70, 0x80000
	v_lshl_add_u64 v[206:207], s[70:71], 0, v[162:163]
	s_addc_u32 s9, s71, 0
	s_add_i32 s10, s10, s80
	global_load_lds_dwordx4 v[206:207], off
	v_lshl_add_u64 v[2:3], s[8:9], 0, v[158:159]
	s_mov_b32 m0, s10
	v_lshl_add_u64 v[222:223], vcc, 0, v[156:157]
	global_load_lds_dwordx4 v[2:3], off
	v_lshl_add_u64 v[2:3], s[8:9], 0, v[162:163]
	s_add_i32 m0, s10, 0x2000
	v_lshl_add_u64 v[224:225], vcc, 0, v[160:161]
	global_load_lds_dwordx4 v[2:3], off
	s_mov_b32 m0, s58
	s_nop 0
	global_load_lds_dwordx4 v[222:223], off
	s_mov_b32 m0, s12
	s_nop 0
	global_load_lds_dwordx4 v[224:225], off
	s_waitcnt vmcnt(8)
	s_waitcnt lgkmcnt(0)
	s_barrier
	s_waitcnt lgkmcnt(0)
	v_mfma_f32_16x16x32_bf16 v[72:75], v[52:55], v[176:179], 0
	v_mfma_f32_16x16x32_bf16 v[64:67], v[76:79], v[176:179], 0
	v_mfma_f32_16x16x32_bf16 v[60:63], v[76:79], v[190:193], 0
	v_mfma_f32_16x16x32_bf16 v[68:71], v[52:55], v[190:193], 0
	v_mfma_f32_16x16x32_bf16 v[48:51], v[52:55], v[198:201], 0
	v_mfma_f32_16x16x32_bf16 v[44:47], v[76:79], v[198:201], 0
	v_mfma_f32_16x16x32_bf16 v[36:39], v[76:79], v[214:217], 0
	v_mfma_f32_16x16x32_bf16 v[40:43], v[52:55], v[214:217], 0
	v_mfma_f32_16x16x32_bf16 v[72:75], v[56:59], v[180:183], v[72:75]
	v_mfma_f32_16x16x32_bf16 v[64:67], v[80:83], v[180:183], v[64:67]
	v_mfma_f32_16x16x32_bf16 v[60:63], v[80:83], v[194:197], v[60:63]
	v_mfma_f32_16x16x32_bf16 v[68:71], v[56:59], v[194:197], v[68:71]
	v_mfma_f32_16x16x32_bf16 v[48:51], v[56:59], v[210:213], v[48:51]
	v_mfma_f32_16x16x32_bf16 v[44:47], v[80:83], v[210:213], v[44:47]
	v_mfma_f32_16x16x32_bf16 v[36:39], v[80:83], v[218:221], v[36:39]
	v_mfma_f32_16x16x32_bf16 v[40:43], v[56:59], v[218:221], v[40:43]
	v_mfma_f32_16x16x32_bf16 v[32:35], v[116:119], v[176:179], 0
	v_mfma_f32_16x16x32_bf16 v[24:27], v[168:171], v[176:179], 0
	v_mfma_f32_16x16x32_bf16 v[20:23], v[168:171], v[190:193], 0
	v_mfma_f32_16x16x32_bf16 v[28:31], v[116:119], v[190:193], 0
	v_mfma_f32_16x16x32_bf16 v[16:19], v[116:119], v[198:201], 0
	v_mfma_f32_16x16x32_bf16 v[12:15], v[168:171], v[198:201], 0
	v_mfma_f32_16x16x32_bf16 v[2:5], v[168:171], v[214:217], 0
	v_mfma_f32_16x16x32_bf16 v[8:11], v[116:119], v[214:217], 0
	v_mfma_f32_16x16x32_bf16 v[32:35], v[120:123], v[180:183], v[32:35]
	v_mfma_f32_16x16x32_bf16 v[24:27], v[172:175], v[180:183], v[24:27]
	v_mfma_f32_16x16x32_bf16 v[20:23], v[172:175], v[194:197], v[20:23]
	v_mfma_f32_16x16x32_bf16 v[28:31], v[120:123], v[194:197], v[28:31]
	v_mfma_f32_16x16x32_bf16 v[16:19], v[120:123], v[210:213], v[16:19]
	v_mfma_f32_16x16x32_bf16 v[12:15], v[172:175], v[210:213], v[12:15]
	v_mfma_f32_16x16x32_bf16 v[2:5], v[172:175], v[218:221], v[2:5]
	v_mfma_f32_16x16x32_bf16 v[8:11], v[120:123], v[218:221], v[8:11]
	s_barrier
; #define PG8_STAGE(bufoff, gbase, voff) do { _Pragma("unroll") for (int _i = 0; _i < 2; ++_i) \
;         __builtin_amdgcn_global_load_lds((const unsigned*)((const char*)(gbase) + (voff)[_i]), (PG8_LAS unsigned*)(lds + (bufoff) + ldsw + _i * 8192), 16, 0, 0); } while (0)
; #define PG8_LDA(dst, b, h) do { _Pragma("unroll") for (int m = 0; m < 4; ++m) _Pragma("unroll") for (int k = 0; k < 2; ++k) dst[m][k] = *(const PG8_LAS bf16x8*)(lds + PG8_SA(b, h) + aoff + m * 2048 + k * 1024); } while (0)
; #define PG8_LDB(dst, b, h) do { _Pragma("unroll") for (int n = 0; n < 2; ++n) _Pragma("unroll") for (int k = 0; k < 2; ++k) dst[n][k] = *(const PG8_LAS bf16x8*)(lds + PG8_SB(b, h) + boff + n * 2048 + k * 1024); } while (0)
; #define PG8_MMA(ai, bj, At, Bt) do { __builtin_amdgcn_s_setprio(1); _Pragma("unroll") for (int m = 0; m < 4; ++m) _Pragma("unroll") for (int n = 0; n < 2; ++n) _Pragma("unroll") for (int k = 0; k < 2; ++k) \
;         acc[ai][bj][m][n] = mma16<Epi::I8>(Bt[n][k], At[m][k], acc[ai][bj][m][n]); __builtin_amdgcn_s_setprio(0); } while (0)
; #define PG8_WAIT_V(n) asm volatile("s_waitcnt vmcnt(" #n ")" ::: "memory")
; #define PG8_WAIT_L(n) asm volatile("s_waitcnt lgkmcnt(" #n ")" ::: "memory")
; #define PG8_BAR __builtin_amdgcn_s_barrier()
; #define PG8_SCHED __builtin_amdgcn_sched_barrier(0)
; template <class Epi, class Sched, bool ALIGN_EPI = false, bool SP2 = false>
; __device__ __forceinline__ void gemm_phase(PG8_LAS unsigned char* lds, const Gemm g, const Sched& S, const Epi& E) {
;     ...
;         for (int t = 0; t < nt; t += 2) {
;     ...
;             PG8_LDB(B0, 1, 0); PG8_LDB(B1, 1, 1); PG8_SCHED; PG8_LDA(At, 1, 0); PG8_STAGE(PG8_SA(0, 1), a2 + hstep, voffA);
;             PG8_WAIT_V(8); PG8_WAIT_L(0); PG8_BAR; PG8_MMA(0, 0, At, B0); PG8_MMA(0, 1, At, B1); PG8_BAR; PG8_SCHED;
;             PG8_LDA(At, 1, 1); PG8_STAGE(PG8_SB(1, 0), b3, voffB); PG8_STAGE(PG8_SB(1, 1), b3 + hstep, voffB); PG8_STAGE(PG8_SA(1, 0), a3, voffA);
;             PG8_WAIT_V(8); PG8_WAIT_L(0); PG8_BAR; PG8_MMA(1, 0, At, B0); PG8_MMA(1, 1, At, B1); PG8_BAR; PG8_SCHED;
	s_add_i32 s10, 0, 0x18000
	v_add_u32_e32 v0, s10, v188
	s_add_i32 s11, 0, 0x1c000
	ds_read_b128 v[52:55], v0
	ds_read_b128 v[56:59], v0 offset:1024
	ds_read_b128 v[76:79], v0 offset:2048
	ds_read_b128 v[80:83], v0 offset:3072
	v_add_u32_e32 v0, s11, v188
	ds_read_b128 v[116:119], v0
	ds_read_b128 v[120:123], v0 offset:1024
	ds_read_b128 v[168:171], v0 offset:2048
	ds_read_b128 v[172:175], v0 offset:3072
	s_add_u32 s8, vcc_lo, 0x80000
	s_addc_u32 s9, vcc_hi, 0
	s_mov_b32 m0, s13
	v_lshl_add_u64 v[6:7], s[8:9], 0, v[156:157]
	ds_read_b128 v[176:179], v189 offset:32768
	ds_read_b128 v[180:183], v189 offset:33792
	ds_read_b128 v[190:193], v189 offset:34816
	ds_read_b128 v[194:197], v189 offset:35840
	ds_read_b128 v[198:201], v189 offset:36864
	ds_read_b128 v[210:213], v189 offset:37888
	ds_read_b128 v[214:217], v189 offset:38912
	ds_read_b128 v[218:221], v189 offset:39936
	global_load_lds_dwordx4 v[6:7], off
	v_lshl_add_u64 v[6:7], s[8:9], 0, v[160:161]
	s_mov_b32 m0, s66
	s_nop 0
	global_load_lds_dwordx4 v[6:7], off
	s_waitcnt vmcnt(8)
	s_waitcnt lgkmcnt(0)
	s_barrier
	s_waitcnt lgkmcnt(0)
	v_mfma_f32_16x16x32_bf16 v[152:155], v[52:55], v[176:179], v[152:155]
	v_mfma_f32_16x16x32_bf16 v[144:147], v[76:79], v[176:179], v[144:147]
	v_mfma_f32_16x16x32_bf16 v[140:143], v[76:79], v[190:193], v[140:143]
	v_mfma_f32_16x16x32_bf16 v[148:151], v[52:55], v[190:193], v[148:151]
	v_mfma_f32_16x16x32_bf16 v[136:139], v[52:55], v[198:201], v[136:139]
	v_mfma_f32_16x16x32_bf16 v[132:135], v[76:79], v[198:201], v[132:135]
	v_mfma_f32_16x16x32_bf16 v[124:127], v[76:79], v[214:217], v[124:127]
	v_mfma_f32_16x16x32_bf16 v[128:131], v[52:55], v[214:217], v[128:131]
	v_mfma_f32_16x16x32_bf16 v[152:155], v[56:59], v[180:183], v[152:155]
	v_mfma_f32_16x16x32_bf16 v[144:147], v[80:83], v[180:183], v[144:147]
	v_mfma_f32_16x16x32_bf16 v[140:143], v[80:83], v[194:197], v[140:143]
	v_mfma_f32_16x16x32_bf16 v[148:151], v[56:59], v[194:197], v[148:151]
	v_mfma_f32_16x16x32_bf16 v[136:139], v[56:59], v[210:213], v[136:139]
	v_mfma_f32_16x16x32_bf16 v[132:135], v[80:83], v[210:213], v[132:135]
	v_mfma_f32_16x16x32_bf16 v[124:127], v[80:83], v[218:221], v[124:127]
	v_mfma_f32_16x16x32_bf16 v[128:131], v[56:59], v[218:221], v[128:131]
	v_mfma_f32_16x16x32_bf16 v[112:115], v[116:119], v[176:179], v[112:115]
	v_mfma_f32_16x16x32_bf16 v[104:107], v[168:171], v[176:179], v[104:107]
	v_mfma_f32_16x16x32_bf16 v[100:103], v[168:171], v[190:193], v[100:103]
	v_mfma_f32_16x16x32_bf16 v[108:111], v[116:119], v[190:193], v[108:111]
	v_mfma_f32_16x16x32_bf16 v[96:99], v[116:119], v[198:201], v[96:99]
	v_mfma_f32_16x16x32_bf16 v[92:95], v[168:171], v[198:201], v[92:95]
	v_mfma_f32_16x16x32_bf16 v[84:87], v[168:171], v[214:217], v[84:87]
	v_mfma_f32_16x16x32_bf16 v[88:91], v[116:119], v[214:217], v[88:91]
	v_mfma_f32_16x16x32_bf16 v[112:115], v[120:123], v[180:183], v[112:115]
	v_mfma_f32_16x16x32_bf16 v[104:107], v[172:175], v[180:183], v[104:107]
	v_mfma_f32_16x16x32_bf16 v[100:103], v[172:175], v[194:197], v[100:103]
	v_mfma_f32_16x16x32_bf16 v[108:111], v[120:123], v[194:197], v[108:111]
	v_mfma_f32_16x16x32_bf16 v[96:99], v[120:123], v[210:213], v[96:99]
	v_mfma_f32_16x16x32_bf16 v[92:95], v[172:175], v[210:213], v[92:95]
	v_mfma_f32_16x16x32_bf16 v[84:87], v[172:175], v[218:221], v[84:87]
	v_mfma_f32_16x16x32_bf16 v[88:91], v[120:123], v[218:221], v[88:91]
	s_barrier
	s_add_i32 s8, s10, s80
	v_lshl_add_u64 v[6:7], v[184:185], 0, s[92:93]
	s_mov_b32 m0, s8
	ds_read_b128 v[176:179], v189 offset:49152
	ds_read_b128 v[180:183], v189 offset:50176
	ds_read_b128 v[190:193], v189 offset:51200
	ds_read_b128 v[194:197], v189 offset:52224
	ds_read_b128 v[198:201], v189 offset:53248
	ds_read_b128 v[210:213], v189 offset:54272
	ds_read_b128 v[214:217], v189 offset:55296
	ds_read_b128 v[218:221], v189 offset:56320
	global_load_lds_dwordx4 v[6:7], off
	s_add_i32 m0, s8, 0x2000
	s_add_u32 s8, s70, 0x80080
	v_lshl_add_u64 v[6:7], v[206:207], 0, s[92:93]
	s_addc_u32 s9, s71, 0
	s_add_i32 s10, s11, s80
	global_load_lds_dwordx4 v[6:7], off
	v_lshl_add_u64 v[6:7], s[8:9], 0, v[158:159]
	s_mov_b32 m0, s10
	s_nop 0
	global_load_lds_dwordx4 v[6:7], off
	v_lshl_add_u64 v[6:7], s[8:9], 0, v[162:163]
	s_add_i32 m0, s10, 0x2000
	s_nop 0
	global_load_lds_dwordx4 v[6:7], off
	v_lshl_add_u64 v[6:7], v[222:223], 0, s[92:93]
	s_mov_b32 m0, s67
	s_nop 0
	global_load_lds_dwordx4 v[6:7], off
	v_lshl_add_u64 v[6:7], v[224:225], 0, s[92:93]
	s_mov_b32 m0, s81
	s_nop 0
	global_load_lds_dwordx4 v[6:7], off
	s_waitcnt vmcnt(8)
	s_waitcnt lgkmcnt(0)
	s_barrier
	s_waitcnt lgkmcnt(0)
	v_mfma_f32_16x16x32_bf16 v[72:75], v[52:55], v[176:179], v[72:75]
	v_mfma_f32_16x16x32_bf16 v[64:67], v[76:79], v[176:179], v[64:67]
	v_mfma_f32_16x16x32_bf16 v[60:63], v[76:79], v[190:193], v[60:63]
	v_mfma_f32_16x16x32_bf16 v[68:71], v[52:55], v[190:193], v[68:71]
	v_mfma_f32_16x16x32_bf16 v[48:51], v[52:55], v[198:201], v[48:51]
	v_mfma_f32_16x16x32_bf16 v[44:47], v[76:79], v[198:201], v[44:47]
	v_mfma_f32_16x16x32_bf16 v[36:39], v[76:79], v[214:217], v[36:39]
	v_mfma_f32_16x16x32_bf16 v[40:43], v[52:55], v[214:217], v[40:43]
	v_mfma_f32_16x16x32_bf16 v[72:75], v[56:59], v[180:183], v[72:75]
	v_mfma_f32_16x16x32_bf16 v[64:67], v[80:83], v[180:183], v[64:67]
	v_mfma_f32_16x16x32_bf16 v[60:63], v[80:83], v[194:197], v[60:63]
	v_mfma_f32_16x16x32_bf16 v[68:71], v[56:59], v[194:197], v[68:71]
	v_mfma_f32_16x16x32_bf16 v[48:51], v[56:59], v[210:213], v[48:51]
	v_mfma_f32_16x16x32_bf16 v[44:47], v[80:83], v[210:213], v[44:47]
	v_mfma_f32_16x16x32_bf16 v[36:39], v[80:83], v[218:221], v[36:39]
	v_mfma_f32_16x16x32_bf16 v[40:43], v[56:59], v[218:221], v[40:43]
	v_mfma_f32_16x16x32_bf16 v[32:35], v[116:119], v[176:179], v[32:35]
	v_mfma_f32_16x16x32_bf16 v[24:27], v[168:171], v[176:179], v[24:27]
	v_mfma_f32_16x16x32_bf16 v[20:23], v[168:171], v[190:193], v[20:23]
	v_mfma_f32_16x16x32_bf16 v[28:31], v[116:119], v[190:193], v[28:31]
	v_mfma_f32_16x16x32_bf16 v[16:19], v[116:119], v[198:201], v[16:19]
	v_mfma_f32_16x16x32_bf16 v[12:15], v[168:171], v[198:201], v[12:15]
	v_mfma_f32_16x16x32_bf16 v[2:5], v[168:171], v[214:217], v[2:5]
	v_mfma_f32_16x16x32_bf16 v[6:9], v[116:119], v[214:217], v[8:11]
	v_mfma_f32_16x16x32_bf16 v[32:35], v[120:123], v[180:183], v[32:35]
	v_mfma_f32_16x16x32_bf16 v[24:27], v[172:175], v[180:183], v[24:27]
	v_mfma_f32_16x16x32_bf16 v[20:23], v[172:175], v[194:197], v[20:23]
	v_mfma_f32_16x16x32_bf16 v[28:31], v[120:123], v[194:197], v[28:31]
	v_mfma_f32_16x16x32_bf16 v[16:19], v[120:123], v[210:213], v[16:19]
	v_mfma_f32_16x16x32_bf16 v[12:15], v[172:175], v[210:213], v[12:15]
	v_mfma_f32_16x16x32_bf16 v[8:11], v[120:123], v[218:221], v[6:9]
	v_mfma_f32_16x16x32_bf16 v[4:7], v[172:175], v[218:221], v[2:5]
	s_barrier
	s_add_i32 s4, s4, 2
	s_add_u32 s97, s97, 0x100
	s_addc_u32 s96, s96, 0
	s_cmp_gt_u32 s4, 29
	s_mov_b64 s[8:9], s[68:69]
	s_cbranch_scc0 .LBB0_327
	s_branch .Lpeelx327
	.p2align	6

; #define PG8_STAGE(bufoff, gbase, voff) do { _Pragma("unroll") for (int _i = 0; _i < 2; ++_i) \
;         __builtin_amdgcn_global_load_lds((const unsigned*)((const char*)(gbase) + (voff)[_i]), (PG8_LAS unsigned*)(lds + (bufoff) + ldsw + _i * 8192), 16, 0, 0); } while (0)
; #define PG8_LDA(dst, b, h) do { _Pragma("unroll") for (int m = 0; m < 4; ++m) _Pragma("unroll") for (int k = 0; k < 2; ++k) dst[m][k] = *(const PG8_LAS bf16x8*)(lds + PG8_SA(b, h) + aoff + m * 2048 + k * 1024); } while (0)
; #define PG8_LDB(dst, b, h) do { _Pragma("unroll") for (int n = 0; n < 2; ++n) _Pragma("unroll") for (int k = 0; k < 2; ++k) dst[n][k] = *(const PG8_LAS bf16x8*)(lds + PG8_SB(b, h) + boff + n * 2048 + k * 1024); } while (0)
; #define PG8_MMA(ai, bj, At, Bt) do { __builtin_amdgcn_s_setprio(1); _Pragma("unroll") for (int m = 0; m < 4; ++m) _Pragma("unroll") for (int n = 0; n < 2; ++n) _Pragma("unroll") for (int k = 0; k < 2; ++k) \
;         acc[ai][bj][m][n] = mma16<Epi::I8>(Bt[n][k], At[m][k], acc[ai][bj][m][n]); __builtin_amdgcn_s_setprio(0); } while (0)
; #define PG8_WAIT_V(n) asm volatile("s_waitcnt vmcnt(" #n ")" ::: "memory")
; #define PG8_WAIT_L(n) asm volatile("s_waitcnt lgkmcnt(" #n ")" ::: "memory")
; #define PG8_BAR __builtin_amdgcn_s_barrier()
; template <class Epi, class Sched, bool ALIGN_EPI = false, bool SP2 = false>
; __device__ __forceinline__ void gemm_phase(PG8_LAS unsigned char* lds, const Gemm g, const Sched& S, const Epi& E) {
;     ...
;             const bool last = (t == nt - 2);
;             const char* a1 = cA + (size_t)(t + 1) * kstep;
;             const char* a2 = last ? nA : cA + (size_t)(t + 2) * kstep; const char* b2 = last ? nB : cB + (size_t)(t + 2) * kstep;
;             const char* a3 = a2 + kstep; const char* b3 = b2 + kstep;
;             if (last && has_next) S.a_ready(nxt);
;             if constexpr (SP2) {
;             PG8_LDB(B0, 0, 0); PG8_LDB(B1, 0, 1); PG8_SCHED; PG8_LDA(At, 0, 0); PG8_STAGE(PG8_SA(1, 1), a1 + hstep, voffA);
;             PG8_WAIT_V(8); PG8_WAIT_L(0); PG8_BAR; PG8_MMA(0, 0, At, B0); PG8_MMA(0, 1, At, B1); PG8_BAR; PG8_SCHED;
;             PG8_LDA(At, 0, 1); PG8_STAGE(PG8_SB(0, 0), b2, voffB); PG8_STAGE(PG8_SB(0, 1), b2 + hstep, voffB); PG8_STAGE(PG8_SA(0, 0), a2, voffA);
;             PG8_WAIT_V(8); PG8_WAIT_L(0); PG8_BAR; PG8_MMA(1, 0, At, B0); PG8_MMA(1, 1, At, B1); PG8_BAR; PG8_SCHED;
.Lpeel385:
	s_add_u32 s70, s8, 0x100
	s_addc_u32 s71, s9, 0
	s_add_i32 s84, 0, 0x10000
	s_cmp_eq_u32 s5, 12
	s_cselect_b32 vcc_hi, s1, s71
	s_cselect_b32 vcc_lo, s7, s70
	v_add_u32_e32 v0, s84, v214
	s_cselect_b32 s83, s69, s68
	s_cselect_b32 s82, s81, s85
	s_add_i32 s10, 0, 0x14000
	ds_read_b128 v[44:47], v0
	ds_read_b128 v[52:55], v0 offset:1024
	ds_read_b128 v[60:63], v0 offset:2048
	ds_read_b128 v[64:67], v0 offset:3072
	v_add_u32_e32 v0, s10, v214
	ds_read_b128 v[84:87], v0
	ds_read_b128 v[88:91], v0 offset:1024
	ds_read_b128 v[92:95], v0 offset:2048
	ds_read_b128 v[100:103], v0 offset:3072
	v_lshl_add_u64 v[2:3], s[8:9], 0, v[184:185]
	s_add_i32 m0, s13, 0xc000
	ds_read_b128 v[124:127], v215
	ds_read_b128 v[128:131], v215 offset:1024
	ds_read_b128 v[140:143], v215 offset:2048
	ds_read_b128 v[188:191], v215 offset:3072
	ds_read_b128 v[192:195], v215 offset:4096
	ds_read_b128 v[196:199], v215 offset:5120
	ds_read_b128 v[216:219], v215 offset:6144
	ds_read_b128 v[220:223], v215 offset:7168
	global_load_lds_dwordx4 v[2:3], off
	v_lshl_add_u64 v[2:3], s[8:9], 0, v[186:187]
	s_add_i32 m0, s13, 0xe000
	s_nop 0
	global_load_lds_dwordx4 v[2:3], off
	s_waitcnt vmcnt(8)
	s_waitcnt lgkmcnt(0)
	s_barrier
	s_waitcnt lgkmcnt(0)
	v_mfma_i32_16x16x64_i8 v[172:175], v[44:47], v[124:127], 0
	v_mfma_i32_16x16x64_i8 v[164:167], v[60:63], v[124:127], 0
	v_mfma_i32_16x16x64_i8 v[160:163], v[60:63], v[140:143], 0
	v_mfma_i32_16x16x64_i8 v[168:171], v[44:47], v[140:143], 0
	v_mfma_i32_16x16x64_i8 v[156:159], v[44:47], v[192:195], 0
	v_mfma_i32_16x16x64_i8 v[152:155], v[60:63], v[192:195], 0
	v_mfma_i32_16x16x64_i8 v[144:147], v[60:63], v[216:219], 0
	v_mfma_i32_16x16x64_i8 v[148:151], v[44:47], v[216:219], 0
	v_mfma_i32_16x16x64_i8 v[172:175], v[52:55], v[128:131], v[172:175]
	v_mfma_i32_16x16x64_i8 v[164:167], v[64:67], v[128:131], v[164:167]
	v_mfma_i32_16x16x64_i8 v[160:163], v[64:67], v[188:191], v[160:163]
	v_mfma_i32_16x16x64_i8 v[168:171], v[52:55], v[188:191], v[168:171]
	v_mfma_i32_16x16x64_i8 v[156:159], v[52:55], v[196:199], v[156:159]
	v_mfma_i32_16x16x64_i8 v[152:155], v[64:67], v[196:199], v[152:155]
	v_mfma_i32_16x16x64_i8 v[144:147], v[64:67], v[220:223], v[144:147]
	v_mfma_i32_16x16x64_i8 v[148:151], v[52:55], v[220:223], v[148:151]
	v_mfma_i32_16x16x64_i8 v[136:139], v[84:87], v[124:127], 0
	v_mfma_i32_16x16x64_i8 v[120:123], v[92:95], v[124:127], 0
	v_mfma_i32_16x16x64_i8 v[116:119], v[92:95], v[140:143], 0
	v_mfma_i32_16x16x64_i8 v[108:111], v[92:95], v[192:195], 0
	v_mfma_i32_16x16x64_i8 v[112:115], v[84:87], v[192:195], 0
	v_mfma_i32_16x16x64_i8 v[104:107], v[84:87], v[216:219], 0
	v_mfma_i32_16x16x64_i8 v[96:99], v[92:95], v[216:219], 0
	v_mfma_i32_16x16x64_i8 v[136:139], v[88:91], v[128:131], v[136:139]
	v_mfma_i32_16x16x64_i8 v[120:123], v[100:103], v[128:131], v[120:123]
	v_mfma_i32_16x16x64_i8 v[116:119], v[100:103], v[188:191], v[116:119]
	v_mfma_i32_16x16x64_i8 v[108:111], v[100:103], v[196:199], v[108:111]
	v_mfma_i32_16x16x64_i8 v[112:115], v[88:91], v[196:199], v[112:115]
	v_mfma_i32_16x16x64_i8 v[104:107], v[88:91], v[220:223], v[104:107]
	v_mfma_i32_16x16x64_i8 v[96:99], v[100:103], v[220:223], v[96:99]
	v_mfma_i32_16x16x64_i8 v[124:127], v[84:87], v[140:143], 0
	v_mfma_i32_16x16x64_i8 v[124:127], v[88:91], v[188:191], v[124:127]
	s_barrier
	s_add_i32 s8, s84, s12
	v_lshl_add_u64 v[200:201], s[82:83], 0, v[178:179]
	s_mov_b32 m0, s8
	ds_read_b128 v[128:131], v215 offset:16384
	ds_read_b128 v[132:135], v215 offset:17408
	ds_read_b128 v[140:143], v215 offset:18432
	ds_read_b128 v[188:191], v215 offset:19456
	ds_read_b128 v[192:195], v215 offset:20480
	ds_read_b128 v[196:199], v215 offset:21504
	ds_read_b128 v[216:219], v215 offset:22528
	ds_read_b128 v[220:223], v215 offset:23552
	global_load_lds_dwordx4 v[200:201], off
	s_add_i32 m0, s8, 0x2000
	s_add_u32 s8, s82, 0x40000
	v_lshl_add_u64 v[206:207], s[82:83], 0, v[182:183]
	s_addc_u32 s9, s83, 0
	s_add_i32 s10, s10, s12
	global_load_lds_dwordx4 v[206:207], off
	v_lshl_add_u64 v[2:3], s[8:9], 0, v[178:179]
	s_mov_b32 m0, s10
	v_lshl_add_u64 v[210:211], vcc, 0, v[176:177]
	global_load_lds_dwordx4 v[2:3], off
	v_lshl_add_u64 v[2:3], s[8:9], 0, v[182:183]
	s_add_i32 m0, s10, 0x2000
	v_lshl_add_u64 v[224:225], vcc, 0, v[180:181]
	global_load_lds_dwordx4 v[2:3], off
	s_mov_b32 m0, s13
	s_nop 0
	global_load_lds_dwordx4 v[210:211], off
	s_mov_b32 m0, s66
	s_nop 0
	global_load_lds_dwordx4 v[224:225], off
	s_waitcnt vmcnt(8)
	s_waitcnt lgkmcnt(0)
	s_barrier
	s_waitcnt lgkmcnt(0)
	v_mfma_i32_16x16x64_i8 v[80:83], v[44:47], v[128:131], 0
	v_mfma_i32_16x16x64_i8 v[72:75], v[60:63], v[128:131], 0
	v_mfma_i32_16x16x64_i8 v[68:71], v[60:63], v[140:143], 0
	v_mfma_i32_16x16x64_i8 v[76:79], v[44:47], v[140:143], 0
	v_mfma_i32_16x16x64_i8 v[56:59], v[44:47], v[192:195], 0
	v_mfma_i32_16x16x64_i8 v[48:51], v[60:63], v[192:195], 0
	v_mfma_i32_16x16x64_i8 v[36:39], v[60:63], v[216:219], 0
	v_mfma_i32_16x16x64_i8 v[40:43], v[44:47], v[216:219], 0
	v_mfma_i32_16x16x64_i8 v[80:83], v[52:55], v[132:135], v[80:83]
	v_mfma_i32_16x16x64_i8 v[72:75], v[64:67], v[132:135], v[72:75]
	v_mfma_i32_16x16x64_i8 v[68:71], v[64:67], v[188:191], v[68:71]
	v_mfma_i32_16x16x64_i8 v[76:79], v[52:55], v[188:191], v[76:79]
	v_mfma_i32_16x16x64_i8 v[56:59], v[52:55], v[196:199], v[56:59]
	v_mfma_i32_16x16x64_i8 v[48:51], v[64:67], v[196:199], v[48:51]
	v_mfma_i32_16x16x64_i8 v[36:39], v[64:67], v[220:223], v[36:39]
	v_mfma_i32_16x16x64_i8 v[40:43], v[52:55], v[220:223], v[40:43]
	v_mfma_i32_16x16x64_i8 v[32:35], v[84:87], v[128:131], 0
	v_mfma_i32_16x16x64_i8 v[24:27], v[92:95], v[128:131], 0
	v_mfma_i32_16x16x64_i8 v[20:23], v[92:95], v[140:143], 0
	v_mfma_i32_16x16x64_i8 v[28:31], v[84:87], v[140:143], 0
	v_mfma_i32_16x16x64_i8 v[16:19], v[84:87], v[192:195], 0
	v_mfma_i32_16x16x64_i8 v[12:15], v[92:95], v[192:195], 0
	v_mfma_i32_16x16x64_i8 v[2:5], v[92:95], v[216:219], 0
	v_mfma_i32_16x16x64_i8 v[8:11], v[84:87], v[216:219], 0
	v_mfma_i32_16x16x64_i8 v[32:35], v[88:91], v[132:135], v[32:35]
	v_mfma_i32_16x16x64_i8 v[24:27], v[100:103], v[132:135], v[24:27]
	v_mfma_i32_16x16x64_i8 v[20:23], v[100:103], v[188:191], v[20:23]
	v_mfma_i32_16x16x64_i8 v[28:31], v[88:91], v[188:191], v[28:31]
	v_mfma_i32_16x16x64_i8 v[16:19], v[88:91], v[196:199], v[16:19]
	v_mfma_i32_16x16x64_i8 v[12:15], v[100:103], v[196:199], v[12:15]
	v_mfma_i32_16x16x64_i8 v[2:5], v[100:103], v[220:223], v[2:5]
	v_mfma_i32_16x16x64_i8 v[8:11], v[88:91], v[220:223], v[8:11]
	s_barrier
; #define PG8_STAGE(bufoff, gbase, voff) do { _Pragma("unroll") for (int _i = 0; _i < 2; ++_i) \
;         __builtin_amdgcn_global_load_lds((const unsigned*)((const char*)(gbase) + (voff)[_i]), (PG8_LAS unsigned*)(lds + (bufoff) + ldsw + _i * 8192), 16, 0, 0); } while (0)
; #define PG8_LDA(dst, b, h) do { _Pragma("unroll") for (int m = 0; m < 4; ++m) _Pragma("unroll") for (int k = 0; k < 2; ++k) dst[m][k] = *(const PG8_LAS bf16x8*)(lds + PG8_SA(b, h) + aoff + m * 2048 + k * 1024); } while (0)
; #define PG8_LDB(dst, b, h) do { _Pragma("unroll") for (int n = 0; n < 2; ++n) _Pragma("unroll") for (int k = 0; k < 2; ++k) dst[n][k] = *(const PG8_LAS bf16x8*)(lds + PG8_SB(b, h) + boff + n * 2048 + k * 1024); } while (0)
; #define PG8_MMA(ai, bj, At, Bt) do { __builtin_amdgcn_s_setprio(1); _Pragma("unroll") for (int m = 0; m < 4; ++m) _Pragma("unroll") for (int n = 0; n < 2; ++n) _Pragma("unroll") for (int k = 0; k < 2; ++k) \
;         acc[ai][bj][m][n] = mma16<Epi::I8>(Bt[n][k], At[m][k], acc[ai][bj][m][n]); __builtin_amdgcn_s_setprio(0); } while (0)
; #define PG8_WAIT_V(n) asm volatile("s_waitcnt vmcnt(" #n ")" ::: "memory")
; #define PG8_WAIT_L(n) asm volatile("s_waitcnt lgkmcnt(" #n ")" ::: "memory")
; #define PG8_BAR __builtin_amdgcn_s_barrier()
; #define PG8_SCHED __builtin_amdgcn_sched_barrier(0)
; template <class Epi, class Sched, bool ALIGN_EPI = false, bool SP2 = false>
; __device__ __forceinline__ void gemm_phase(PG8_LAS unsigned char* lds, const Gemm g, const Sched& S, const Epi& E) {
;     ...
;         for (int t = 0; t < nt; t += 2) {
;     ...
;             PG8_LDB(B0, 1, 0); PG8_LDB(B1, 1, 1); PG8_SCHED; PG8_LDA(At, 1, 0); PG8_STAGE(PG8_SA(0, 1), a2 + hstep, voffA);
;             PG8_WAIT_V(8); PG8_WAIT_L(0); PG8_BAR; PG8_MMA(0, 0, At, B0); PG8_MMA(0, 1, At, B1); PG8_BAR; PG8_SCHED;
;             PG8_LDA(At, 1, 1); PG8_STAGE(PG8_SB(1, 0), b3, voffB); PG8_STAGE(PG8_SB(1, 1), b3 + hstep, voffB); PG8_STAGE(PG8_SA(1, 0), a3, voffA);
;             PG8_WAIT_V(8); PG8_WAIT_L(0); PG8_BAR; PG8_MMA(1, 0, At, B0); PG8_MMA(1, 1, At, B1); PG8_BAR; PG8_SCHED;
	s_add_i32 s10, 0, 0x18000
	v_add_u32_e32 v0, s10, v214
	s_add_i32 s11, 0, 0x1c000
	ds_read_b128 v[44:47], v0
	ds_read_b128 v[52:55], v0 offset:1024
	ds_read_b128 v[60:63], v0 offset:2048
	ds_read_b128 v[64:67], v0 offset:3072
	v_add_u32_e32 v0, s11, v214
	ds_read_b128 v[84:87], v0
	ds_read_b128 v[88:91], v0 offset:1024
	ds_read_b128 v[92:95], v0 offset:2048
	ds_read_b128 v[100:103], v0 offset:3072
	s_add_u32 s8, vcc_lo, 0x40000
	s_addc_u32 s9, vcc_hi, 0
	s_mov_b32 m0, s67
	v_lshl_add_u64 v[6:7], s[8:9], 0, v[176:177]
	ds_read_b128 v[128:131], v215 offset:32768
	ds_read_b128 v[132:135], v215 offset:33792
	ds_read_b128 v[140:143], v215 offset:34816
	ds_read_b128 v[188:191], v215 offset:35840
	ds_read_b128 v[192:195], v215 offset:36864
	ds_read_b128 v[196:199], v215 offset:37888
	ds_read_b128 v[216:219], v215 offset:38912
	ds_read_b128 v[220:223], v215 offset:39936
	global_load_lds_dwordx4 v[6:7], off
	v_lshl_add_u64 v[6:7], s[8:9], 0, v[180:181]
	s_mov_b32 m0, s80
	s_nop 0
	global_load_lds_dwordx4 v[6:7], off
	s_waitcnt vmcnt(8)
	s_waitcnt lgkmcnt(0)
	s_barrier
	s_waitcnt lgkmcnt(0)
	v_mfma_i32_16x16x64_i8 v[172:175], v[44:47], v[128:131], v[172:175]
	v_mfma_i32_16x16x64_i8 v[164:167], v[60:63], v[128:131], v[164:167]
	v_mfma_i32_16x16x64_i8 v[160:163], v[60:63], v[140:143], v[160:163]
	v_mfma_i32_16x16x64_i8 v[168:171], v[44:47], v[140:143], v[168:171]
	v_mfma_i32_16x16x64_i8 v[156:159], v[44:47], v[192:195], v[156:159]
	v_mfma_i32_16x16x64_i8 v[152:155], v[60:63], v[192:195], v[152:155]
	v_mfma_i32_16x16x64_i8 v[144:147], v[60:63], v[216:219], v[144:147]
	v_mfma_i32_16x16x64_i8 v[148:151], v[44:47], v[216:219], v[148:151]
	v_mfma_i32_16x16x64_i8 v[172:175], v[52:55], v[132:135], v[172:175]
	v_mfma_i32_16x16x64_i8 v[164:167], v[64:67], v[132:135], v[164:167]
	v_mfma_i32_16x16x64_i8 v[160:163], v[64:67], v[188:191], v[160:163]
	v_mfma_i32_16x16x64_i8 v[168:171], v[52:55], v[188:191], v[168:171]
	v_mfma_i32_16x16x64_i8 v[156:159], v[52:55], v[196:199], v[156:159]
	v_mfma_i32_16x16x64_i8 v[152:155], v[64:67], v[196:199], v[152:155]
	v_mfma_i32_16x16x64_i8 v[144:147], v[64:67], v[220:223], v[144:147]
	v_mfma_i32_16x16x64_i8 v[148:151], v[52:55], v[220:223], v[148:151]
	v_mfma_i32_16x16x64_i8 v[136:139], v[84:87], v[128:131], v[136:139]
	v_mfma_i32_16x16x64_i8 v[120:123], v[92:95], v[128:131], v[120:123]
	v_mfma_i32_16x16x64_i8 v[116:119], v[92:95], v[140:143], v[116:119]
	v_mfma_i32_16x16x64_i8 v[124:127], v[84:87], v[140:143], v[124:127]
	v_mfma_i32_16x16x64_i8 v[112:115], v[84:87], v[192:195], v[112:115]
	v_mfma_i32_16x16x64_i8 v[108:111], v[92:95], v[192:195], v[108:111]
	v_mfma_i32_16x16x64_i8 v[96:99], v[92:95], v[216:219], v[96:99]
	v_mfma_i32_16x16x64_i8 v[104:107], v[84:87], v[216:219], v[104:107]
	v_mfma_i32_16x16x64_i8 v[136:139], v[88:91], v[132:135], v[136:139]
	v_mfma_i32_16x16x64_i8 v[120:123], v[100:103], v[132:135], v[120:123]
	v_mfma_i32_16x16x64_i8 v[116:119], v[100:103], v[188:191], v[116:119]
	v_mfma_i32_16x16x64_i8 v[132:135], v[88:91], v[188:191], v[124:127]
	v_mfma_i32_16x16x64_i8 v[112:115], v[88:91], v[196:199], v[112:115]
	v_mfma_i32_16x16x64_i8 v[108:111], v[100:103], v[196:199], v[108:111]
	v_mfma_i32_16x16x64_i8 v[96:99], v[100:103], v[220:223], v[96:99]
	v_mfma_i32_16x16x64_i8 v[104:107], v[88:91], v[220:223], v[104:107]
	s_barrier
	s_add_i32 s8, s10, s12
	v_lshl_add_u64 v[6:7], v[200:201], 0, s[92:93]
	s_mov_b32 m0, s8
	ds_read_b128 v[124:127], v215 offset:49152
	ds_read_b128 v[128:131], v215 offset:50176
	ds_read_b128 v[140:143], v215 offset:51200
	ds_read_b128 v[188:191], v215 offset:52224
	ds_read_b128 v[192:195], v215 offset:53248
	ds_read_b128 v[196:199], v215 offset:54272
	ds_read_b128 v[216:219], v215 offset:55296
	ds_read_b128 v[220:223], v215 offset:56320
	global_load_lds_dwordx4 v[6:7], off
	s_add_i32 m0, s8, 0x2000
	s_add_u32 s8, s82, 0x40080
	v_lshl_add_u64 v[6:7], v[206:207], 0, s[92:93]
	s_addc_u32 s9, s83, 0
	s_add_i32 s10, s11, s12
	global_load_lds_dwordx4 v[6:7], off
	v_lshl_add_u64 v[6:7], s[8:9], 0, v[178:179]
	s_mov_b32 m0, s10
	s_nop 0
	global_load_lds_dwordx4 v[6:7], off
	v_lshl_add_u64 v[6:7], s[8:9], 0, v[182:183]
	s_add_i32 m0, s10, 0x2000
	s_nop 0
	global_load_lds_dwordx4 v[6:7], off
	v_lshl_add_u64 v[6:7], v[210:211], 0, s[92:93]
	s_mov_b32 m0, s58
	s_nop 0
	global_load_lds_dwordx4 v[6:7], off
	v_lshl_add_u64 v[6:7], v[224:225], 0, s[92:93]
	s_mov_b32 m0, s4
	s_nop 0
	global_load_lds_dwordx4 v[6:7], off
	s_waitcnt vmcnt(8)
	s_waitcnt lgkmcnt(0)
	s_barrier
	s_waitcnt lgkmcnt(0)
	v_mfma_i32_16x16x64_i8 v[80:83], v[44:47], v[124:127], v[80:83]
	v_mfma_i32_16x16x64_i8 v[72:75], v[60:63], v[124:127], v[72:75]
	v_mfma_i32_16x16x64_i8 v[68:71], v[60:63], v[140:143], v[68:71]
	v_mfma_i32_16x16x64_i8 v[76:79], v[44:47], v[140:143], v[76:79]
	v_mfma_i32_16x16x64_i8 v[56:59], v[44:47], v[192:195], v[56:59]
	v_mfma_i32_16x16x64_i8 v[48:51], v[60:63], v[192:195], v[48:51]
	v_mfma_i32_16x16x64_i8 v[36:39], v[60:63], v[216:219], v[36:39]
	v_mfma_i32_16x16x64_i8 v[40:43], v[44:47], v[216:219], v[40:43]
	v_mfma_i32_16x16x64_i8 v[80:83], v[52:55], v[128:131], v[80:83]
	v_mfma_i32_16x16x64_i8 v[72:75], v[64:67], v[128:131], v[72:75]
	v_mfma_i32_16x16x64_i8 v[68:71], v[64:67], v[188:191], v[68:71]
	v_mfma_i32_16x16x64_i8 v[76:79], v[52:55], v[188:191], v[76:79]
	v_mfma_i32_16x16x64_i8 v[56:59], v[52:55], v[196:199], v[56:59]
	v_mfma_i32_16x16x64_i8 v[48:51], v[64:67], v[196:199], v[48:51]
	v_mfma_i32_16x16x64_i8 v[36:39], v[64:67], v[220:223], v[36:39]
	v_mfma_i32_16x16x64_i8 v[40:43], v[52:55], v[220:223], v[40:43]
	v_mfma_i32_16x16x64_i8 v[32:35], v[84:87], v[124:127], v[32:35]
	v_mfma_i32_16x16x64_i8 v[24:27], v[92:95], v[124:127], v[24:27]
	v_mfma_i32_16x16x64_i8 v[20:23], v[92:95], v[140:143], v[20:23]
	v_mfma_i32_16x16x64_i8 v[28:31], v[84:87], v[140:143], v[28:31]
	v_mfma_i32_16x16x64_i8 v[16:19], v[84:87], v[192:195], v[16:19]
	v_mfma_i32_16x16x64_i8 v[12:15], v[92:95], v[192:195], v[12:15]
	v_mfma_i32_16x16x64_i8 v[2:5], v[92:95], v[216:219], v[2:5]
	v_mfma_i32_16x16x64_i8 v[6:9], v[84:87], v[216:219], v[8:11]
	v_mfma_i32_16x16x64_i8 v[32:35], v[88:91], v[128:131], v[32:35]
	v_mfma_i32_16x16x64_i8 v[24:27], v[100:103], v[128:131], v[24:27]
	v_mfma_i32_16x16x64_i8 v[20:23], v[100:103], v[188:191], v[20:23]
	v_mfma_i32_16x16x64_i8 v[28:31], v[88:91], v[188:191], v[28:31]
	v_mfma_i32_16x16x64_i8 v[16:19], v[88:91], v[196:199], v[16:19]
	v_mfma_i32_16x16x64_i8 v[12:15], v[100:103], v[196:199], v[12:15]
	v_mfma_i32_16x16x64_i8 v[8:11], v[88:91], v[220:223], v[6:9]
	v_mfma_i32_16x16x64_i8 v[4:7], v[100:103], v[220:223], v[2:5]
	s_barrier
	s_add_i32 s5, s5, 2
	s_add_u32 s85, s85, 0x100
	s_addc_u32 s68, s68, 0
	s_cmp_gt_u32 s5, 13
	s_mov_b64 s[8:9], s[70:71]
	s_cbranch_scc0 .LBB0_385
	s_branch .Lpeelx385
	.p2align	6
